# SwiGLU phases: next unit's first LDS-DMA pair issued at the epilogue top (ahead of the epilogue stores in the in-order VMEM queue), first-iteration waits of follow-on units relaxed to leave the stores
# baseline (speedup 1.0000x reference)
; #define PG8_STAGE(bufoff, gbase, voff) do { _Pragma("unroll") for (int _i = 0; _i < 2; ++_i) \
;         __builtin_amdgcn_global_load_lds((const unsigned*)((const char*)(gbase) + (voff)[_i]), (PG8_LAS unsigned*)(lds + (bufoff) + ldsw + _i * 8192), 16, 0, 0); } while (0)
; #define PG8_WAIT_V(n) asm volatile("s_waitcnt vmcnt(" #n ")" ::: "memory")
; #define PG8_BAR __builtin_amdgcn_s_barrier()
; template <class Epi, class Sched, bool ALIGN_EPI = false, bool SP2 = false>
; __device__ __forceinline__ void gemm_phase(PG8_LAS unsigned char* lds, const Gemm g, const Sched& S, const Epi& E) {
;     const int tid = threadIdx.x, wid = __builtin_amdgcn_readfirstlane(tid >> 6), lane = tid & 63, wr = wid >> 2, wc = wid & 3, fr = lane & 15, fq = lane >> 4;
;     const int K = g.K, nt = K / BK;
;     unsigned voffA[2], voffB[2];
; #pragma unroll
;     for (int i = 0; i < 2; ++i) { int R, C; stage_rc(tid * 16 + i * 8192, R, C); const int Rb = Epi::PERM ? ((R & ~31) + perm32(R & 31)) : R;
;         voffA[i] = (unsigned)(R * K + C) * 2u; voffB[i] = (unsigned)(Rb * K + C) * 2u; }
;     const size_t kstep = (size_t)(BK * 2);
;     const size_t hstep = (size_t)HALF * K * 2;
;     const size_t tstep = 2 * hstep;
;     const unsigned ldsw = (unsigned)wid * 1024u;
;     const int aoff = lds_byte(wr * 64 + fr, fq * 8), boff = lds_byte(wc * 32 + fr, fq * 8);
;     ...
;         PG8_WAIT_V(2); PG8_BAR;
;         PG8_STAGE(PG8_SB(1, 0), cB + kstep, voffB); PG8_STAGE(PG8_SA(1, 0), cA + kstep, voffA); PG8_STAGE(PG8_SB(1, 1), cB + hstep + kstep, voffB);
;         PG8_WAIT_V(6); PG8_BAR;
.LBB0_226:
	s_mul_i32 s15, s15, s8
	s_sub_i32 s9, s9, s15
	s_sub_i32 s15, s9, s8
	s_cmp_ge_u32 s9, s8
	s_cselect_b32 s9, s15, s9
	s_sub_i32 s15, s9, s8
	s_cmp_ge_u32 s9, s8
	s_cselect_b32 s8, s15, s9
	s_xor_b32 s8, s8, s3
	s_sub_i32 s18, s8, s3
	s_add_u32 s8, s12, 0x500000
	s_addc_u32 s9, s13, 0
	s_ashr_i32 s19, s18, 31
	s_and_b64 s[20:21], s[30:31], exec
	s_cselect_b32 s15, 25, 28
	s_lshl_b64 s[20:21], s[18:19], s15
	s_add_u32 s15, s12, s20
	s_addc_u32 s17, s13, s21
	s_and_b64 s[12:13], s[30:31], exec
	s_cselect_b32 s12, 12, 15
	s_lshl_b64 s[12:13], s[18:19], s12
	s_mul_hi_u32 s18, s12, 0xffffea00
	s_sub_i32 s18, s18, s12
	s_mulk_i32 s13, 0xea00
	s_add_i32 s18, s18, s13
	s_mulk_i32 s12, 0xea00
	s_add_u32 s12, s15, s12
	s_addc_u32 s13, s17, s18
	s_add_u32 s12, s12, 0xa000000
	s_addc_u32 s13, s13, 0
	s_lshl_b32 s14, s14, 5
	s_and_b32 s20, s14, 0x60
	s_mov_b64 s[14:15], 0x80
	s_add_i32 m0, s37, 0x18000
	v_lshl_add_u64 v[6:7], v[6:7], 0, s[14:15]
	s_lshl_b32 s17, s16, 13
	s_lshl_b32 s21, s20, 7
	s_waitcnt vmcnt(2)
	s_barrier
	global_load_lds_dwordx4 v[6:7], off
	v_lshl_add_u64 v[4:5], v[4:5], 0, s[14:15]
	s_add_i32 m0, s37, 0x1a000
	s_add_i32 s54, s37, 0x8000
	s_add_i32 s55, s37, 0xa000
	global_load_lds_dwordx4 v[4:5], off
	v_lshl_add_u64 v[0:1], v[0:1], 0, s[14:15]
	s_mov_b32 m0, s54
	s_add_u32 s18, s40, 0x40080
	global_load_lds_dwordx4 v[0:1], off
	v_lshl_add_u64 v[0:1], v[2:3], 0, s[14:15]
	s_mov_b32 m0, s55
	s_addc_u32 s19, s41, 0
	global_load_lds_dwordx4 v[0:1], off
	s_add_i32 m0, s37, 0x1c000
	v_lshl_add_u64 v[0:1], s[18:19], 0, v[132:133]
	global_load_lds_dwordx4 v[0:1], off
	v_lshl_add_u64 v[0:1], s[18:19], 0, v[128:129]
	s_add_i32 m0, s37, 0x1e000
	s_sext_i32_i16 s63, s4
	global_load_lds_dwordx4 v[0:1], off
	v_and_b32_e32 v0, 15, v242
	v_lshlrev_b32_e32 v1, 1, v11
	v_lshlrev_b32_e32 v2, 2, v242
	v_lshlrev_b32_e32 v3, 6, v242
	s_movk_i32 s4, 0x3c0
	v_lshl_or_b32 v146, s16, 6, v0
	v_lshl_or_b32 v0, v0, 6, v1
	v_and_b32_e32 v2, 32, v2
	v_and_or_b32 v1, v3, s4, v1
	v_bitop3_b32 v147, s21, v1, v2 bitop3:0xf6
	v_lshlrev_b32_e32 v1, 8, v242
	v_bitop3_b32 v0, v0, s17, v2 bitop3:0xde
	v_and_b32_e32 v1, 0x38000, v1
	v_lshlrev_b32_e32 v2, 11, v12
	v_or3_b32 v1, v9, v1, v2
	v_add_u32_e32 v136, v1, v10
	v_lshlrev_b32_e32 v1, 4, v8
	s_waitcnt vmcnt(6)
	s_cmpk_lt_u32 s5, 0x100
	v_and_b32_e32 v1, 0x78000, v1
	s_cselect_b64 s[16:17], -1, 0
	v_or3_b32 v1, v9, v1, v2
	s_add_i32 s57, 0, 0x10000
	s_add_i32 s58, 0, 0x14000
	s_ashr_i32 s56, s61, 31
	v_or_b32_e32 v148, s20, v11
	v_mov_b32_e32 v137, v133
	v_add_u32_e32 v138, v1, v10
	v_mov_b32_e32 v139, v133
	v_mov_b64_e32 v[140:141], 0xb00
	v_mov_b64_e32 v[142:143], 0xaff
	v_add_u32_e32 v149, s57, v147
	v_add_u32_e32 v150, s58, v147
	v_add_u32_e32 v151, 0, v0
	v_mov_b32_e32 v152, 0x358637bd
	s_movk_i32 s59, 0x1600
	s_barrier
	s_mov_b32 s99, 1
	s_branch .LBB0_229

; #define PG8_STAGE(bufoff, gbase, voff) do { _Pragma("unroll") for (int _i = 0; _i < 2; ++_i) \
;         __builtin_amdgcn_global_load_lds((const unsigned*)((const char*)(gbase) + (voff)[_i]), (PG8_LAS unsigned*)(lds + (bufoff) + ldsw + _i * 8192), 16, 0, 0); } while (0)
; #define PG8_LDA(dst, b, h) do { _Pragma("unroll") for (int m = 0; m < 4; ++m) _Pragma("unroll") for (int k = 0; k < 2; ++k) dst[m][k] = *(const PG8_LAS bf16x8*)(lds + PG8_SA(b, h) + aoff + m * 2048 + k * 1024); } while (0)
; #define PG8_LDB(dst, b, h) do { _Pragma("unroll") for (int n = 0; n < 2; ++n) _Pragma("unroll") for (int k = 0; k < 2; ++k) dst[n][k] = *(const PG8_LAS bf16x8*)(lds + PG8_SB(b, h) + boff + n * 2048 + k * 1024); } while (0)
; #define PG8_WAIT_V(n) asm volatile("s_waitcnt vmcnt(" #n ")" ::: "memory")
; #define PG8_WAIT_L(n) asm volatile("s_waitcnt lgkmcnt(" #n ")" ::: "memory")
; template <class Epi, class Sched, bool ALIGN_EPI = false, bool SP2 = false>
; __device__ __forceinline__ void gemm_phase(PG8_LAS unsigned char* lds, const Gemm g, const Sched& S, const Epi& E) {
;     ...
;         const bool has_next = S.next(ui + 1, nxt);
;         const char* nA = has_next ? (const char*)g.A + (size_t)nxt.pm * tstep : cA; const char* nB = has_next ? (const char*)g.Bt + (size_t)nxt.pn * tstep : cB;
;         for (int t = 0; t < nt; t += 2) {
;             const bool last = (t == nt - 2);
;             if constexpr (Epi::PREFETCH) { if (t == nt - 4) E.prefetch(cur, lds + STAGE_BYTES + 1024, tid); }
;             const char* a1 = cA + (size_t)(t + 1) * kstep;
;             const char* a2 = last ? nA : cA + (size_t)(t + 2) * kstep; const char* b2 = last ? nB : cB + (size_t)(t + 2) * kstep;
;             const char* a3 = a2 + kstep; const char* b3 = b2 + kstep;
;             if (last && has_next) S.a_ready(nxt);
;             if constexpr (SP2) {
;             PG8_LDB(B0, 0, 0); PG8_LDB(B1, 0, 1); PG8_SCHED; PG8_LDA(At, 0, 0); PG8_STAGE(PG8_SA(1, 1), a1 + hstep, voffA);
;             PG8_WAIT_V(8); PG8_WAIT_L(0); PG8_BAR; PG8_MMA(0, 0, At, B0); PG8_MMA(0, 1, At, B1); PG8_BAR; PG8_SCHED;
;             PG8_LDA(At, 0, 1); PG8_STAGE(PG8_SB(0, 0), b2, voffB); PG8_STAGE(PG8_SB(0, 1), b2 + hstep, voffB); PG8_STAGE(PG8_SA(0, 0), a2, voffA);
;             PG8_WAIT_V(8); PG8_WAIT_L(0); PG8_BAR; PG8_MMA(1, 0, At, B0); PG8_MMA(1, 1, At, B1); PG8_BAR; PG8_SCHED;
.LBB0_231:
	s_ashr_i32 s21, s20, 31
	s_lshl_b64 s[22:23], s[20:21], 19
	s_add_u32 s22, s44, s22
	s_addc_u32 s23, s45, s23
	s_and_b64 s[34:35], s[4:5], exec
	s_cselect_b32 s21, s23, s39
	s_cselect_b32 s64, s22, s38
	s_ashr_i32 s19, s18, 31
	s_lshl_b64 s[34:35], s[18:19], 19
	s_add_u32 s34, s46, s34
	s_addc_u32 s35, s47, s35
	s_and_b64 s[42:43], s[4:5], exec
	s_cselect_b32 s19, s35, s41
	s_cselect_b32 s65, s34, s40
	s_add_u32 s38, s38, 0x40080
	s_addc_u32 s39, s39, 0
	s_add_u32 s66, s40, 0x100
	s_addc_u32 s67, s41, 0
	s_mov_b32 s68, -2
	s_cmp_eq_u32 s99, 0
	s_cbranch_scc1 .Lpeel_hoisted_0
	s_mov_b32 s99, 0
	ds_read_b128 v[154:157], v149
	ds_read_b128 v[158:161], v149 offset:1024
	ds_read_b128 v[162:165], v149 offset:2048
	ds_read_b128 v[166:169], v149 offset:3072
	ds_read_b128 v[170:173], v150
	ds_read_b128 v[174:177], v150 offset:1024
	ds_read_b128 v[178:181], v150 offset:2048
	ds_read_b128 v[182:185], v150 offset:3072
	s_add_u32 s40, s38, 0xfffc0080
	s_addc_u32 s41, s39, -1
	s_cmp_eq_u32 s68, 12
	s_cselect_b32 s43, s21, s41
	s_cselect_b32 s42, s64, s40
	s_cselect_b32 s41, s19, s67
	s_cselect_b32 s40, s65, s66
	v_lshl_add_u64 v[144:145], s[38:39], 0, v[136:137]
	s_add_i32 m0, s37, 0xc000
	ds_read_b128 v[186:189], v151
	ds_read_b128 v[190:193], v151 offset:1024
	ds_read_b128 v[194:197], v151 offset:2048
	ds_read_b128 v[198:201], v151 offset:3072
	ds_read_b128 v[202:205], v151 offset:4096
	ds_read_b128 v[206:209], v151 offset:5120
	ds_read_b128 v[210:213], v151 offset:6144
	ds_read_b128 v[214:217], v151 offset:7168
	global_load_lds_dwordx4 v[144:145], off
	v_lshl_add_u64 v[144:145], s[38:39], 0, v[138:139]
	s_add_i32 m0, s37, 0xe000
	s_nop 0
	global_load_lds_dwordx4 v[144:145], off
	s_waitcnt vmcnt(8)
	s_waitcnt lgkmcnt(0)
	s_barrier
	s_setprio 1
	v_mfma_f32_16x16x32_bf16 v[120:123], v[154:157], v[186:189], 0
	v_mfma_f32_16x16x32_bf16 v[116:119], v[162:165], v[186:189], 0
	v_mfma_f32_16x16x32_bf16 v[108:111], v[154:157], v[194:197], 0
	v_mfma_f32_16x16x32_bf16 v[100:103], v[162:165], v[194:197], 0
	v_mfma_f32_16x16x32_bf16 v[92:95], v[154:157], v[202:205], 0
	v_mfma_f32_16x16x32_bf16 v[84:87], v[162:165], v[202:205], 0
	v_mfma_f32_16x16x32_bf16 v[76:79], v[154:157], v[210:213], 0
	v_mfma_f32_16x16x32_bf16 v[68:71], v[162:165], v[210:213], 0
	v_mfma_f32_16x16x32_bf16 v[120:123], v[158:161], v[190:193], v[120:123]
	v_mfma_f32_16x16x32_bf16 v[116:119], v[166:169], v[190:193], v[116:119]
	v_mfma_f32_16x16x32_bf16 v[108:111], v[158:161], v[198:201], v[108:111]
	v_mfma_f32_16x16x32_bf16 v[100:103], v[166:169], v[198:201], v[100:103]
	v_mfma_f32_16x16x32_bf16 v[92:95], v[158:161], v[206:209], v[92:95]
	v_mfma_f32_16x16x32_bf16 v[84:87], v[166:169], v[206:209], v[84:87]
	v_mfma_f32_16x16x32_bf16 v[76:79], v[158:161], v[214:217], v[76:79]
	v_mfma_f32_16x16x32_bf16 v[68:71], v[166:169], v[214:217], v[68:71]
	v_mfma_f32_16x16x32_bf16 v[124:127], v[170:173], v[186:189], 0
	v_mfma_f32_16x16x32_bf16 v[112:115], v[178:181], v[186:189], 0
	v_mfma_f32_16x16x32_bf16 v[104:107], v[170:173], v[194:197], 0
	v_mfma_f32_16x16x32_bf16 v[96:99], v[178:181], v[194:197], 0
	v_mfma_f32_16x16x32_bf16 v[88:91], v[170:173], v[202:205], 0
	v_mfma_f32_16x16x32_bf16 v[80:83], v[178:181], v[202:205], 0
	v_mfma_f32_16x16x32_bf16 v[72:75], v[170:173], v[210:213], 0
	v_mfma_f32_16x16x32_bf16 v[64:67], v[178:181], v[210:213], 0
	v_mfma_f32_16x16x32_bf16 v[124:127], v[174:177], v[190:193], v[124:127]
	v_mfma_f32_16x16x32_bf16 v[112:115], v[182:185], v[190:193], v[112:115]
	v_mfma_f32_16x16x32_bf16 v[104:107], v[174:177], v[198:201], v[104:107]
	v_mfma_f32_16x16x32_bf16 v[96:99], v[182:185], v[198:201], v[96:99]
	v_mfma_f32_16x16x32_bf16 v[88:91], v[174:177], v[206:209], v[88:91]
	v_mfma_f32_16x16x32_bf16 v[80:83], v[182:185], v[206:209], v[80:83]
	v_mfma_f32_16x16x32_bf16 v[72:75], v[174:177], v[214:217], v[72:75]
	v_mfma_f32_16x16x32_bf16 v[64:67], v[182:185], v[214:217], v[64:67]
	s_barrier
	s_setprio 0
	s_add_i32 s69, s57, s48
	v_lshl_add_u64 v[144:145], s[40:41], 0, v[132:133]
	s_mov_b32 m0, s69
	ds_read_b128 v[186:189], v151 offset:16384
	ds_read_b128 v[190:193], v151 offset:17408
	ds_read_b128 v[194:197], v151 offset:18432
	ds_read_b128 v[198:201], v151 offset:19456
	ds_read_b128 v[202:205], v151 offset:20480
	ds_read_b128 v[206:209], v151 offset:21504
	ds_read_b128 v[210:213], v151 offset:22528
	ds_read_b128 v[214:217], v151 offset:23552
	global_load_lds_dwordx4 v[144:145], off
	s_add_i32 m0, s69, 0x2000
	s_add_u32 s70, s40, 0x40000
	v_lshl_add_u64 v[218:219], s[40:41], 0, v[128:129]
	s_addc_u32 s71, s41, 0
	s_add_i32 s69, s58, s48
	global_load_lds_dwordx4 v[218:219], off
	v_lshl_add_u64 v[220:221], s[70:71], 0, v[132:133]
	s_mov_b32 m0, s69
	v_lshl_add_u64 v[222:223], s[42:43], 0, v[130:131]
	global_load_lds_dwordx4 v[220:221], off
	v_lshl_add_u64 v[220:221], s[70:71], 0, v[128:129]
	s_add_i32 m0, s69, 0x2000
	s_nop 0
	global_load_lds_dwordx4 v[220:221], off
	v_lshl_add_u64 v[220:221], s[42:43], 0, v[134:135]
	s_mov_b32 m0, s37
	s_nop 0
	global_load_lds_dwordx4 v[220:221], off
	s_mov_b32 m0, s50
	s_nop 0
	global_load_lds_dwordx4 v[222:223], off
	s_waitcnt vmcnt(8)
	s_waitcnt lgkmcnt(0)
	s_barrier
; #define PG8_STAGE(bufoff, gbase, voff) do { _Pragma("unroll") for (int _i = 0; _i < 2; ++_i) \
;         __builtin_amdgcn_global_load_lds((const unsigned*)((const char*)(gbase) + (voff)[_i]), (PG8_LAS unsigned*)(lds + (bufoff) + ldsw + _i * 8192), 16, 0, 0); } while (0)
; #define PG8_LDA(dst, b, h) do { _Pragma("unroll") for (int m = 0; m < 4; ++m) _Pragma("unroll") for (int k = 0; k < 2; ++k) dst[m][k] = *(const PG8_LAS bf16x8*)(lds + PG8_SA(b, h) + aoff + m * 2048 + k * 1024); } while (0)
; #define PG8_LDB(dst, b, h) do { _Pragma("unroll") for (int n = 0; n < 2; ++n) _Pragma("unroll") for (int k = 0; k < 2; ++k) dst[n][k] = *(const PG8_LAS bf16x8*)(lds + PG8_SB(b, h) + boff + n * 2048 + k * 1024); } while (0)
; #define PG8_MMA(ai, bj, At, Bt) do { __builtin_amdgcn_s_setprio(1); _Pragma("unroll") for (int m = 0; m < 4; ++m) _Pragma("unroll") for (int n = 0; n < 2; ++n) _Pragma("unroll") for (int k = 0; k < 2; ++k) \
;         acc[ai][bj][m][n] = __builtin_amdgcn_mfma_f32_16x16x32_bf16(Bt[n][k], At[m][k], acc[ai][bj][m][n], 0, 0, 0); __builtin_amdgcn_s_setprio(0); } while (0)
; #define PG8_WAIT_V(n) asm volatile("s_waitcnt vmcnt(" #n ")" ::: "memory")
; #define PG8_WAIT_L(n) asm volatile("s_waitcnt lgkmcnt(" #n ")" ::: "memory")
; #define PG8_BAR __builtin_amdgcn_s_barrier()
; #define PG8_SCHED __builtin_amdgcn_sched_barrier(0)
; template <class Epi, class Sched, bool ALIGN_EPI = false, bool SP2 = false>
; __device__ __forceinline__ void gemm_phase(PG8_LAS unsigned char* lds, const Gemm g, const Sched& S, const Epi& E) {
;     ...
;             PG8_WAIT_V(8); PG8_WAIT_L(0); PG8_BAR; PG8_MMA(0, 0, At, B0); PG8_MMA(0, 1, At, B1); PG8_BAR; PG8_SCHED;
;             PG8_LDA(At, 0, 1); PG8_STAGE(PG8_SB(0, 0), b2, voffB); PG8_STAGE(PG8_SB(0, 1), b2 + hstep, voffB); PG8_STAGE(PG8_SA(0, 0), a2, voffA);
;             PG8_WAIT_V(8); PG8_WAIT_L(0); PG8_BAR; PG8_MMA(1, 0, At, B0); PG8_MMA(1, 1, At, B1); PG8_BAR; PG8_SCHED;
;             PG8_LDB(B0, 1, 0); PG8_LDB(B1, 1, 1); PG8_SCHED; PG8_LDA(At, 1, 0); PG8_STAGE(PG8_SA(0, 1), a2 + hstep, voffA);
;             PG8_WAIT_V(8); PG8_WAIT_L(0); PG8_BAR; PG8_MMA(0, 0, At, B0); PG8_MMA(0, 1, At, B1); PG8_BAR; PG8_SCHED;
	s_setprio 1
	v_mfma_f32_16x16x32_bf16 v[60:63], v[154:157], v[186:189], 0
	v_mfma_f32_16x16x32_bf16 v[52:55], v[162:165], v[186:189], 0
	v_mfma_f32_16x16x32_bf16 v[44:47], v[154:157], v[194:197], 0
	v_mfma_f32_16x16x32_bf16 v[36:39], v[162:165], v[194:197], 0
	v_mfma_f32_16x16x32_bf16 v[28:31], v[154:157], v[202:205], 0
	v_mfma_f32_16x16x32_bf16 v[20:23], v[162:165], v[202:205], 0
	v_mfma_f32_16x16x32_bf16 v[12:15], v[154:157], v[210:213], 0
	v_mfma_f32_16x16x32_bf16 v[4:7], v[162:165], v[210:213], 0
	v_mfma_f32_16x16x32_bf16 v[60:63], v[158:161], v[190:193], v[60:63]
	v_mfma_f32_16x16x32_bf16 v[52:55], v[166:169], v[190:193], v[52:55]
	v_mfma_f32_16x16x32_bf16 v[44:47], v[158:161], v[198:201], v[44:47]
	v_mfma_f32_16x16x32_bf16 v[36:39], v[166:169], v[198:201], v[36:39]
	v_mfma_f32_16x16x32_bf16 v[28:31], v[158:161], v[206:209], v[28:31]
	v_mfma_f32_16x16x32_bf16 v[20:23], v[166:169], v[206:209], v[20:23]
	v_mfma_f32_16x16x32_bf16 v[12:15], v[158:161], v[214:217], v[12:15]
	v_mfma_f32_16x16x32_bf16 v[4:7], v[166:169], v[214:217], v[4:7]
	v_mfma_f32_16x16x32_bf16 v[56:59], v[170:173], v[186:189], 0
	v_mfma_f32_16x16x32_bf16 v[48:51], v[178:181], v[186:189], 0
	v_mfma_f32_16x16x32_bf16 v[40:43], v[170:173], v[194:197], 0
	v_mfma_f32_16x16x32_bf16 v[32:35], v[178:181], v[194:197], 0
	v_mfma_f32_16x16x32_bf16 v[24:27], v[170:173], v[202:205], 0
	v_mfma_f32_16x16x32_bf16 v[16:19], v[178:181], v[202:205], 0
	v_mfma_f32_16x16x32_bf16 v[8:11], v[170:173], v[210:213], 0
	v_mfma_f32_16x16x32_bf16 v[0:3], v[178:181], v[210:213], 0
	v_mfma_f32_16x16x32_bf16 v[56:59], v[174:177], v[190:193], v[56:59]
	v_mfma_f32_16x16x32_bf16 v[48:51], v[182:185], v[190:193], v[48:51]
	v_mfma_f32_16x16x32_bf16 v[40:43], v[174:177], v[198:201], v[40:43]
	v_mfma_f32_16x16x32_bf16 v[32:35], v[182:185], v[198:201], v[32:35]
	v_mfma_f32_16x16x32_bf16 v[24:27], v[174:177], v[206:209], v[24:27]
	v_mfma_f32_16x16x32_bf16 v[16:19], v[182:185], v[206:209], v[16:19]
	v_mfma_f32_16x16x32_bf16 v[8:11], v[174:177], v[214:217], v[8:11]
	v_mfma_f32_16x16x32_bf16 v[0:3], v[182:185], v[214:217], v[0:3]
	s_barrier
	s_setprio 0
	s_add_i32 s69, 0, 0x18000
	v_add_u32_e32 v153, s69, v147
	s_add_i32 s70, 0, 0x1c000
	ds_read_b128 v[154:157], v153
	ds_read_b128 v[158:161], v153 offset:1024
	ds_read_b128 v[162:165], v153 offset:2048
	ds_read_b128 v[166:169], v153 offset:3072
	v_add_u32_e32 v153, s70, v147
	ds_read_b128 v[170:173], v153
	ds_read_b128 v[174:177], v153 offset:1024
	ds_read_b128 v[178:181], v153 offset:2048
	ds_read_b128 v[182:185], v153 offset:3072
	s_add_u32 s42, s42, 0x40000
	s_addc_u32 s43, s43, 0
	s_mov_b32 m0, s51
	v_lshl_add_u64 v[224:225], s[42:43], 0, v[134:135]
	ds_read_b128 v[186:189], v151 offset:32768
	ds_read_b128 v[190:193], v151 offset:33792
	ds_read_b128 v[194:197], v151 offset:34816
	ds_read_b128 v[198:201], v151 offset:35840
	ds_read_b128 v[202:205], v151 offset:36864
	ds_read_b128 v[206:209], v151 offset:37888
	ds_read_b128 v[210:213], v151 offset:38912
	ds_read_b128 v[214:217], v151 offset:39936
	global_load_lds_dwordx4 v[224:225], off
	v_lshl_add_u64 v[224:225], s[42:43], 0, v[130:131]
	s_mov_b32 m0, s52
	s_nop 0
	global_load_lds_dwordx4 v[224:225], off
	s_waitcnt vmcnt(8)
	s_waitcnt lgkmcnt(0)
	s_barrier
	s_setprio 1
	v_mfma_f32_16x16x32_bf16 v[120:123], v[154:157], v[186:189], v[120:123]
	v_mfma_f32_16x16x32_bf16 v[116:119], v[162:165], v[186:189], v[116:119]
	v_mfma_f32_16x16x32_bf16 v[108:111], v[154:157], v[194:197], v[108:111]
	v_mfma_f32_16x16x32_bf16 v[100:103], v[162:165], v[194:197], v[100:103]
	v_mfma_f32_16x16x32_bf16 v[92:95], v[154:157], v[202:205], v[92:95]
	v_mfma_f32_16x16x32_bf16 v[84:87], v[162:165], v[202:205], v[84:87]
	v_mfma_f32_16x16x32_bf16 v[76:79], v[154:157], v[210:213], v[76:79]
	v_mfma_f32_16x16x32_bf16 v[68:71], v[162:165], v[210:213], v[68:71]
	v_mfma_f32_16x16x32_bf16 v[120:123], v[158:161], v[190:193], v[120:123]
	v_mfma_f32_16x16x32_bf16 v[116:119], v[166:169], v[190:193], v[116:119]
	v_mfma_f32_16x16x32_bf16 v[108:111], v[158:161], v[198:201], v[108:111]
	v_mfma_f32_16x16x32_bf16 v[100:103], v[166:169], v[198:201], v[100:103]
	v_mfma_f32_16x16x32_bf16 v[92:95], v[158:161], v[206:209], v[92:95]
	v_mfma_f32_16x16x32_bf16 v[84:87], v[166:169], v[206:209], v[84:87]
	v_mfma_f32_16x16x32_bf16 v[76:79], v[158:161], v[214:217], v[76:79]
	v_mfma_f32_16x16x32_bf16 v[68:71], v[166:169], v[214:217], v[68:71]
	v_mfma_f32_16x16x32_bf16 v[124:127], v[170:173], v[186:189], v[124:127]
	v_mfma_f32_16x16x32_bf16 v[112:115], v[178:181], v[186:189], v[112:115]
	v_mfma_f32_16x16x32_bf16 v[104:107], v[170:173], v[194:197], v[104:107]
	v_mfma_f32_16x16x32_bf16 v[96:99], v[178:181], v[194:197], v[96:99]
	v_mfma_f32_16x16x32_bf16 v[88:91], v[170:173], v[202:205], v[88:91]
	v_mfma_f32_16x16x32_bf16 v[80:83], v[178:181], v[202:205], v[80:83]
	v_mfma_f32_16x16x32_bf16 v[72:75], v[170:173], v[210:213], v[72:75]
	v_mfma_f32_16x16x32_bf16 v[64:67], v[178:181], v[210:213], v[64:67]
	v_mfma_f32_16x16x32_bf16 v[124:127], v[174:177], v[190:193], v[124:127]
	v_mfma_f32_16x16x32_bf16 v[112:115], v[182:185], v[190:193], v[112:115]
	v_mfma_f32_16x16x32_bf16 v[104:107], v[174:177], v[198:201], v[104:107]
	v_mfma_f32_16x16x32_bf16 v[96:99], v[182:185], v[198:201], v[96:99]
	v_mfma_f32_16x16x32_bf16 v[88:91], v[174:177], v[206:209], v[88:91]
	v_mfma_f32_16x16x32_bf16 v[80:83], v[182:185], v[206:209], v[80:83]
	v_mfma_f32_16x16x32_bf16 v[72:75], v[174:177], v[214:217], v[72:75]
	v_mfma_f32_16x16x32_bf16 v[64:67], v[182:185], v[214:217], v[64:67]
	s_barrier
; #define PG8_STAGE(bufoff, gbase, voff) do { _Pragma("unroll") for (int _i = 0; _i < 2; ++_i) \
;         __builtin_amdgcn_global_load_lds((const unsigned*)((const char*)(gbase) + (voff)[_i]), (PG8_LAS unsigned*)(lds + (bufoff) + ldsw + _i * 8192), 16, 0, 0); } while (0)
; #define PG8_LDA(dst, b, h) do { _Pragma("unroll") for (int m = 0; m < 4; ++m) _Pragma("unroll") for (int k = 0; k < 2; ++k) dst[m][k] = *(const PG8_LAS bf16x8*)(lds + PG8_SA(b, h) + aoff + m * 2048 + k * 1024); } while (0)
; #define PG8_LDB(dst, b, h) do { _Pragma("unroll") for (int n = 0; n < 2; ++n) _Pragma("unroll") for (int k = 0; k < 2; ++k) dst[n][k] = *(const PG8_LAS bf16x8*)(lds + PG8_SB(b, h) + boff + n * 2048 + k * 1024); } while (0)
; #define PG8_MMA(ai, bj, At, Bt) do { __builtin_amdgcn_s_setprio(1); _Pragma("unroll") for (int m = 0; m < 4; ++m) _Pragma("unroll") for (int n = 0; n < 2; ++n) _Pragma("unroll") for (int k = 0; k < 2; ++k) \
;         acc[ai][bj][m][n] = __builtin_amdgcn_mfma_f32_16x16x32_bf16(Bt[n][k], At[m][k], acc[ai][bj][m][n], 0, 0, 0); __builtin_amdgcn_s_setprio(0); } while (0)
; #define PG8_WAIT_V(n) asm volatile("s_waitcnt vmcnt(" #n ")" ::: "memory")
; #define PG8_WAIT_L(n) asm volatile("s_waitcnt lgkmcnt(" #n ")" ::: "memory")
; #define PG8_BAR __builtin_amdgcn_s_barrier()
; #define PG8_SCHED __builtin_amdgcn_sched_barrier(0)
; template <class Epi, class Sched, bool ALIGN_EPI = false, bool SP2 = false>
; __device__ __forceinline__ void gemm_phase(PG8_LAS unsigned char* lds, const Gemm g, const Sched& S, const Epi& E) {
;     ...
;             PG8_LDB(B0, 0, 0); PG8_LDB(B1, 0, 1); PG8_SCHED; PG8_LDA(At, 0, 0); PG8_STAGE(PG8_SA(1, 1), a1 + hstep, voffA);
;             PG8_WAIT_V(8); PG8_WAIT_L(0); PG8_BAR; PG8_MMA(0, 0, At, B0); PG8_MMA(0, 1, At, B1); PG8_BAR; PG8_SCHED;
;     ...
;             PG8_LDA(At, 1, 1); PG8_STAGE(PG8_SB(1, 0), b3, voffB); PG8_STAGE(PG8_SB(1, 1), b3 + hstep, voffB); PG8_STAGE(PG8_SA(1, 0), a3, voffA);
;             PG8_WAIT_V(8); PG8_WAIT_L(0); PG8_BAR; PG8_MMA(1, 0, At, B0); PG8_MMA(1, 1, At, B1); PG8_BAR; PG8_SCHED;
	s_setprio 0
	s_add_i32 s42, s69, s48
	v_lshl_add_u64 v[144:145], v[144:145], 0, s[14:15]
	s_mov_b32 m0, s42
	ds_read_b128 v[186:189], v151 offset:49152
	ds_read_b128 v[190:193], v151 offset:50176
	ds_read_b128 v[194:197], v151 offset:51200
	ds_read_b128 v[198:201], v151 offset:52224
	ds_read_b128 v[202:205], v151 offset:53248
	ds_read_b128 v[206:209], v151 offset:54272
	ds_read_b128 v[210:213], v151 offset:55296
	ds_read_b128 v[214:217], v151 offset:56320
	global_load_lds_dwordx4 v[144:145], off
	s_add_i32 m0, s42, 0x2000
	s_add_u32 s40, s40, 0x40080
	v_lshl_add_u64 v[144:145], v[218:219], 0, s[14:15]
	s_addc_u32 s41, s41, 0
	s_add_i32 s42, s70, s48
	global_load_lds_dwordx4 v[144:145], off
	v_lshl_add_u64 v[144:145], s[40:41], 0, v[132:133]
	s_mov_b32 m0, s42
	s_nop 0
	global_load_lds_dwordx4 v[144:145], off
	v_lshl_add_u64 v[144:145], s[40:41], 0, v[128:129]
	s_add_i32 m0, s42, 0x2000
	s_nop 0
	global_load_lds_dwordx4 v[144:145], off
	v_lshl_add_u64 v[144:145], v[220:221], 0, s[14:15]
	s_mov_b32 m0, s54
	s_nop 0
	global_load_lds_dwordx4 v[144:145], off
	v_lshl_add_u64 v[144:145], v[222:223], 0, s[14:15]
	s_mov_b32 m0, s55
	s_nop 0
	global_load_lds_dwordx4 v[144:145], off
	s_waitcnt vmcnt(8)
	s_waitcnt lgkmcnt(0)
	s_barrier
	s_setprio 1
	v_mfma_f32_16x16x32_bf16 v[60:63], v[154:157], v[186:189], v[60:63]
	v_mfma_f32_16x16x32_bf16 v[52:55], v[162:165], v[186:189], v[52:55]
	v_mfma_f32_16x16x32_bf16 v[44:47], v[154:157], v[194:197], v[44:47]
	v_mfma_f32_16x16x32_bf16 v[36:39], v[162:165], v[194:197], v[36:39]
	v_mfma_f32_16x16x32_bf16 v[28:31], v[154:157], v[202:205], v[28:31]
	v_mfma_f32_16x16x32_bf16 v[20:23], v[162:165], v[202:205], v[20:23]
	v_mfma_f32_16x16x32_bf16 v[12:15], v[154:157], v[210:213], v[12:15]
	v_mfma_f32_16x16x32_bf16 v[4:7], v[162:165], v[210:213], v[4:7]
	v_mfma_f32_16x16x32_bf16 v[60:63], v[158:161], v[190:193], v[60:63]
	v_mfma_f32_16x16x32_bf16 v[52:55], v[166:169], v[190:193], v[52:55]
	v_mfma_f32_16x16x32_bf16 v[44:47], v[158:161], v[198:201], v[44:47]
	v_mfma_f32_16x16x32_bf16 v[36:39], v[166:169], v[198:201], v[36:39]
	v_mfma_f32_16x16x32_bf16 v[28:31], v[158:161], v[206:209], v[28:31]
	v_mfma_f32_16x16x32_bf16 v[20:23], v[166:169], v[206:209], v[20:23]
	v_mfma_f32_16x16x32_bf16 v[12:15], v[158:161], v[214:217], v[12:15]
	v_mfma_f32_16x16x32_bf16 v[4:7], v[166:169], v[214:217], v[4:7]
	v_mfma_f32_16x16x32_bf16 v[56:59], v[170:173], v[186:189], v[56:59]
	v_mfma_f32_16x16x32_bf16 v[48:51], v[178:181], v[186:189], v[48:51]
	v_mfma_f32_16x16x32_bf16 v[40:43], v[170:173], v[194:197], v[40:43]
	v_mfma_f32_16x16x32_bf16 v[32:35], v[178:181], v[194:197], v[32:35]
	v_mfma_f32_16x16x32_bf16 v[24:27], v[170:173], v[202:205], v[24:27]
	v_mfma_f32_16x16x32_bf16 v[16:19], v[178:181], v[202:205], v[16:19]
	v_mfma_f32_16x16x32_bf16 v[8:11], v[170:173], v[210:213], v[8:11]
	v_mfma_f32_16x16x32_bf16 v[0:3], v[178:181], v[210:213], v[0:3]
	v_mfma_f32_16x16x32_bf16 v[56:59], v[174:177], v[190:193], v[56:59]
	v_mfma_f32_16x16x32_bf16 v[48:51], v[182:185], v[190:193], v[48:51]
	v_mfma_f32_16x16x32_bf16 v[40:43], v[174:177], v[198:201], v[40:43]
	v_mfma_f32_16x16x32_bf16 v[32:35], v[182:185], v[198:201], v[32:35]
	v_mfma_f32_16x16x32_bf16 v[24:27], v[174:177], v[206:209], v[24:27]
	v_mfma_f32_16x16x32_bf16 v[16:19], v[182:185], v[206:209], v[16:19]
	v_mfma_f32_16x16x32_bf16 v[8:11], v[174:177], v[214:217], v[8:11]
	v_mfma_f32_16x16x32_bf16 v[0:3], v[182:185], v[214:217], v[0:3]
	s_barrier
	s_setprio 0
	s_add_i32 s68, s68, 2
	s_add_u32 s38, s38, 0x100
	s_addc_u32 s39, s39, 0
	s_add_u32 s66, s66, 0x100
	s_addc_u32 s67, s67, 0
	s_branch .LBB0_232
.Lpeel_hoisted_0:
	ds_read_b128 v[154:157], v149
	ds_read_b128 v[158:161], v149 offset:1024
	ds_read_b128 v[162:165], v149 offset:2048
	ds_read_b128 v[166:169], v149 offset:3072
	ds_read_b128 v[170:173], v150
	ds_read_b128 v[174:177], v150 offset:1024
	ds_read_b128 v[178:181], v150 offset:2048
	ds_read_b128 v[182:185], v150 offset:3072
	s_add_u32 s40, s38, 0xfffc0080
	s_addc_u32 s41, s39, -1
	s_cmp_eq_u32 s68, 12
	s_cselect_b32 s43, s21, s41
	s_cselect_b32 s42, s64, s40
	s_cselect_b32 s41, s19, s67
	s_cselect_b32 s40, s65, s66
	ds_read_b128 v[186:189], v151
	ds_read_b128 v[190:193], v151 offset:1024
	ds_read_b128 v[194:197], v151 offset:2048
	ds_read_b128 v[198:201], v151 offset:3072
	ds_read_b128 v[202:205], v151 offset:4096
	ds_read_b128 v[206:209], v151 offset:5120
	ds_read_b128 v[210:213], v151 offset:6144
	ds_read_b128 v[214:217], v151 offset:7168
	s_waitcnt vmcnt(8)
	s_waitcnt lgkmcnt(0)
	s_barrier
	s_setprio 1
	v_mfma_f32_16x16x32_bf16 v[120:123], v[154:157], v[186:189], 0
	v_mfma_f32_16x16x32_bf16 v[116:119], v[162:165], v[186:189], 0
	v_mfma_f32_16x16x32_bf16 v[108:111], v[154:157], v[194:197], 0
	v_mfma_f32_16x16x32_bf16 v[100:103], v[162:165], v[194:197], 0
	v_mfma_f32_16x16x32_bf16 v[92:95], v[154:157], v[202:205], 0
	v_mfma_f32_16x16x32_bf16 v[84:87], v[162:165], v[202:205], 0
	v_mfma_f32_16x16x32_bf16 v[76:79], v[154:157], v[210:213], 0
	v_mfma_f32_16x16x32_bf16 v[68:71], v[162:165], v[210:213], 0
	v_mfma_f32_16x16x32_bf16 v[120:123], v[158:161], v[190:193], v[120:123]
	v_mfma_f32_16x16x32_bf16 v[116:119], v[166:169], v[190:193], v[116:119]
	v_mfma_f32_16x16x32_bf16 v[108:111], v[158:161], v[198:201], v[108:111]
	v_mfma_f32_16x16x32_bf16 v[100:103], v[166:169], v[198:201], v[100:103]
	v_mfma_f32_16x16x32_bf16 v[92:95], v[158:161], v[206:209], v[92:95]
	v_mfma_f32_16x16x32_bf16 v[84:87], v[166:169], v[206:209], v[84:87]
	v_mfma_f32_16x16x32_bf16 v[76:79], v[158:161], v[214:217], v[76:79]
	v_mfma_f32_16x16x32_bf16 v[68:71], v[166:169], v[214:217], v[68:71]
	v_mfma_f32_16x16x32_bf16 v[124:127], v[170:173], v[186:189], 0
	v_mfma_f32_16x16x32_bf16 v[112:115], v[178:181], v[186:189], 0
	v_mfma_f32_16x16x32_bf16 v[104:107], v[170:173], v[194:197], 0
	v_mfma_f32_16x16x32_bf16 v[96:99], v[178:181], v[194:197], 0
	v_mfma_f32_16x16x32_bf16 v[88:91], v[170:173], v[202:205], 0
	v_mfma_f32_16x16x32_bf16 v[80:83], v[178:181], v[202:205], 0
	v_mfma_f32_16x16x32_bf16 v[72:75], v[170:173], v[210:213], 0
	v_mfma_f32_16x16x32_bf16 v[64:67], v[178:181], v[210:213], 0
	v_mfma_f32_16x16x32_bf16 v[124:127], v[174:177], v[190:193], v[124:127]
	v_mfma_f32_16x16x32_bf16 v[112:115], v[182:185], v[190:193], v[112:115]
	v_mfma_f32_16x16x32_bf16 v[104:107], v[174:177], v[198:201], v[104:107]
	v_mfma_f32_16x16x32_bf16 v[96:99], v[182:185], v[198:201], v[96:99]
	v_mfma_f32_16x16x32_bf16 v[88:91], v[174:177], v[206:209], v[88:91]
	v_mfma_f32_16x16x32_bf16 v[80:83], v[182:185], v[206:209], v[80:83]
	v_mfma_f32_16x16x32_bf16 v[72:75], v[174:177], v[214:217], v[72:75]
	v_mfma_f32_16x16x32_bf16 v[64:67], v[182:185], v[214:217], v[64:67]
	s_barrier
; #define PG8_STAGE(bufoff, gbase, voff) do { _Pragma("unroll") for (int _i = 0; _i < 2; ++_i) \
;         __builtin_amdgcn_global_load_lds((const unsigned*)((const char*)(gbase) + (voff)[_i]), (PG8_LAS unsigned*)(lds + (bufoff) + ldsw + _i * 8192), 16, 0, 0); } while (0)
; #define PG8_LDA(dst, b, h) do { _Pragma("unroll") for (int m = 0; m < 4; ++m) _Pragma("unroll") for (int k = 0; k < 2; ++k) dst[m][k] = *(const PG8_LAS bf16x8*)(lds + PG8_SA(b, h) + aoff + m * 2048 + k * 1024); } while (0)
; #define PG8_LDB(dst, b, h) do { _Pragma("unroll") for (int n = 0; n < 2; ++n) _Pragma("unroll") for (int k = 0; k < 2; ++k) dst[n][k] = *(const PG8_LAS bf16x8*)(lds + PG8_SB(b, h) + boff + n * 2048 + k * 1024); } while (0)
; #define PG8_MMA(ai, bj, At, Bt) do { __builtin_amdgcn_s_setprio(1); _Pragma("unroll") for (int m = 0; m < 4; ++m) _Pragma("unroll") for (int n = 0; n < 2; ++n) _Pragma("unroll") for (int k = 0; k < 2; ++k) \
;         acc[ai][bj][m][n] = __builtin_amdgcn_mfma_f32_16x16x32_bf16(Bt[n][k], At[m][k], acc[ai][bj][m][n], 0, 0, 0); __builtin_amdgcn_s_setprio(0); } while (0)
; #define PG8_WAIT_V(n) asm volatile("s_waitcnt vmcnt(" #n ")" ::: "memory")
; #define PG8_WAIT_L(n) asm volatile("s_waitcnt lgkmcnt(" #n ")" ::: "memory")
; #define PG8_BAR __builtin_amdgcn_s_barrier()
; #define PG8_SCHED __builtin_amdgcn_sched_barrier(0)
; template <class Epi, class Sched, bool ALIGN_EPI = false, bool SP2 = false>
; __device__ __forceinline__ void gemm_phase(PG8_LAS unsigned char* lds, const Gemm g, const Sched& S, const Epi& E) {
;     ...
;             PG8_LDA(At, 0, 1); PG8_STAGE(PG8_SB(0, 0), b2, voffB); PG8_STAGE(PG8_SB(0, 1), b2 + hstep, voffB); PG8_STAGE(PG8_SA(0, 0), a2, voffA);
;             PG8_WAIT_V(8); PG8_WAIT_L(0); PG8_BAR; PG8_MMA(1, 0, At, B0); PG8_MMA(1, 1, At, B1); PG8_BAR; PG8_SCHED;
;             PG8_LDB(B0, 1, 0); PG8_LDB(B1, 1, 1); PG8_SCHED; PG8_LDA(At, 1, 0); PG8_STAGE(PG8_SA(0, 1), a2 + hstep, voffA);
;             PG8_WAIT_V(8); PG8_WAIT_L(0); PG8_BAR; PG8_MMA(0, 0, At, B0); PG8_MMA(0, 1, At, B1); PG8_BAR; PG8_SCHED;
	s_setprio 0
	s_add_i32 s69, s57, s48
	v_lshl_add_u64 v[144:145], s[40:41], 0, v[132:133]
	s_mov_b32 m0, s69
	ds_read_b128 v[186:189], v151 offset:16384
	ds_read_b128 v[190:193], v151 offset:17408
	ds_read_b128 v[194:197], v151 offset:18432
	ds_read_b128 v[198:201], v151 offset:19456
	ds_read_b128 v[202:205], v151 offset:20480
	ds_read_b128 v[206:209], v151 offset:21504
	ds_read_b128 v[210:213], v151 offset:22528
	ds_read_b128 v[214:217], v151 offset:23552
	global_load_lds_dwordx4 v[144:145], off
	s_add_i32 m0, s69, 0x2000
	s_add_u32 s70, s40, 0x40000
	v_lshl_add_u64 v[218:219], s[40:41], 0, v[128:129]
	s_addc_u32 s71, s41, 0
	s_add_i32 s69, s58, s48
	global_load_lds_dwordx4 v[218:219], off
	v_lshl_add_u64 v[220:221], s[70:71], 0, v[132:133]
	s_mov_b32 m0, s69
	v_lshl_add_u64 v[222:223], s[42:43], 0, v[130:131]
	global_load_lds_dwordx4 v[220:221], off
	v_lshl_add_u64 v[220:221], s[70:71], 0, v[128:129]
	s_add_i32 m0, s69, 0x2000
	s_nop 0
	global_load_lds_dwordx4 v[220:221], off
	v_lshl_add_u64 v[220:221], s[42:43], 0, v[134:135]
	s_mov_b32 m0, s37
	s_nop 0
	global_load_lds_dwordx4 v[220:221], off
	s_mov_b32 m0, s50
	s_nop 0
	global_load_lds_dwordx4 v[222:223], off
	s_waitcnt vmcnt(14)
	s_waitcnt lgkmcnt(0)
	s_barrier
	s_setprio 1
	v_mfma_f32_16x16x32_bf16 v[60:63], v[154:157], v[186:189], 0
	v_mfma_f32_16x16x32_bf16 v[52:55], v[162:165], v[186:189], 0
	v_mfma_f32_16x16x32_bf16 v[44:47], v[154:157], v[194:197], 0
	v_mfma_f32_16x16x32_bf16 v[36:39], v[162:165], v[194:197], 0
	v_mfma_f32_16x16x32_bf16 v[28:31], v[154:157], v[202:205], 0
	v_mfma_f32_16x16x32_bf16 v[20:23], v[162:165], v[202:205], 0
	v_mfma_f32_16x16x32_bf16 v[12:15], v[154:157], v[210:213], 0
	v_mfma_f32_16x16x32_bf16 v[4:7], v[162:165], v[210:213], 0
	v_mfma_f32_16x16x32_bf16 v[60:63], v[158:161], v[190:193], v[60:63]
	v_mfma_f32_16x16x32_bf16 v[52:55], v[166:169], v[190:193], v[52:55]
	v_mfma_f32_16x16x32_bf16 v[44:47], v[158:161], v[198:201], v[44:47]
	v_mfma_f32_16x16x32_bf16 v[36:39], v[166:169], v[198:201], v[36:39]
	v_mfma_f32_16x16x32_bf16 v[28:31], v[158:161], v[206:209], v[28:31]
	v_mfma_f32_16x16x32_bf16 v[20:23], v[166:169], v[206:209], v[20:23]
	v_mfma_f32_16x16x32_bf16 v[12:15], v[158:161], v[214:217], v[12:15]
	v_mfma_f32_16x16x32_bf16 v[4:7], v[166:169], v[214:217], v[4:7]
	v_mfma_f32_16x16x32_bf16 v[56:59], v[170:173], v[186:189], 0
	v_mfma_f32_16x16x32_bf16 v[48:51], v[178:181], v[186:189], 0
	v_mfma_f32_16x16x32_bf16 v[40:43], v[170:173], v[194:197], 0
	v_mfma_f32_16x16x32_bf16 v[32:35], v[178:181], v[194:197], 0
	v_mfma_f32_16x16x32_bf16 v[24:27], v[170:173], v[202:205], 0
	v_mfma_f32_16x16x32_bf16 v[16:19], v[178:181], v[202:205], 0
	v_mfma_f32_16x16x32_bf16 v[8:11], v[170:173], v[210:213], 0
	v_mfma_f32_16x16x32_bf16 v[0:3], v[178:181], v[210:213], 0
	v_mfma_f32_16x16x32_bf16 v[56:59], v[174:177], v[190:193], v[56:59]
	v_mfma_f32_16x16x32_bf16 v[48:51], v[182:185], v[190:193], v[48:51]
	v_mfma_f32_16x16x32_bf16 v[40:43], v[174:177], v[198:201], v[40:43]
	v_mfma_f32_16x16x32_bf16 v[32:35], v[182:185], v[198:201], v[32:35]
	v_mfma_f32_16x16x32_bf16 v[24:27], v[174:177], v[206:209], v[24:27]
	v_mfma_f32_16x16x32_bf16 v[16:19], v[182:185], v[206:209], v[16:19]
	v_mfma_f32_16x16x32_bf16 v[8:11], v[174:177], v[214:217], v[8:11]
	v_mfma_f32_16x16x32_bf16 v[0:3], v[182:185], v[214:217], v[0:3]
	s_barrier
	s_setprio 0
	s_add_i32 s69, 0, 0x18000
	v_add_u32_e32 v153, s69, v147
	s_add_i32 s70, 0, 0x1c000
	ds_read_b128 v[154:157], v153
	ds_read_b128 v[158:161], v153 offset:1024
	ds_read_b128 v[162:165], v153 offset:2048
	ds_read_b128 v[166:169], v153 offset:3072
	v_add_u32_e32 v153, s70, v147
	ds_read_b128 v[170:173], v153
	ds_read_b128 v[174:177], v153 offset:1024
	ds_read_b128 v[178:181], v153 offset:2048
	ds_read_b128 v[182:185], v153 offset:3072
	s_add_u32 s42, s42, 0x40000
	s_addc_u32 s43, s43, 0
	s_mov_b32 m0, s51
	v_lshl_add_u64 v[224:225], s[42:43], 0, v[134:135]
	ds_read_b128 v[186:189], v151 offset:32768
	ds_read_b128 v[190:193], v151 offset:33792
	ds_read_b128 v[194:197], v151 offset:34816
	ds_read_b128 v[198:201], v151 offset:35840
	ds_read_b128 v[202:205], v151 offset:36864
	ds_read_b128 v[206:209], v151 offset:37888
	ds_read_b128 v[210:213], v151 offset:38912
	ds_read_b128 v[214:217], v151 offset:39936
	global_load_lds_dwordx4 v[224:225], off
	v_lshl_add_u64 v[224:225], s[42:43], 0, v[130:131]
	s_mov_b32 m0, s52
	s_nop 0
	global_load_lds_dwordx4 v[224:225], off
	s_waitcnt vmcnt(16)
	s_waitcnt lgkmcnt(0)
	s_barrier
; #define PG8_STAGE(bufoff, gbase, voff) do { _Pragma("unroll") for (int _i = 0; _i < 2; ++_i) \
;         __builtin_amdgcn_global_load_lds((const unsigned*)((const char*)(gbase) + (voff)[_i]), (PG8_LAS unsigned*)(lds + (bufoff) + ldsw + _i * 8192), 16, 0, 0); } while (0)
; #define PG8_LDA(dst, b, h) do { _Pragma("unroll") for (int m = 0; m < 4; ++m) _Pragma("unroll") for (int k = 0; k < 2; ++k) dst[m][k] = *(const PG8_LAS bf16x8*)(lds + PG8_SA(b, h) + aoff + m * 2048 + k * 1024); } while (0)
; #define PG8_MMA(ai, bj, At, Bt) do { __builtin_amdgcn_s_setprio(1); _Pragma("unroll") for (int m = 0; m < 4; ++m) _Pragma("unroll") for (int n = 0; n < 2; ++n) _Pragma("unroll") for (int k = 0; k < 2; ++k) \
;         acc[ai][bj][m][n] = __builtin_amdgcn_mfma_f32_16x16x32_bf16(Bt[n][k], At[m][k], acc[ai][bj][m][n], 0, 0, 0); __builtin_amdgcn_s_setprio(0); } while (0)
; #define PG8_WAIT_V(n) asm volatile("s_waitcnt vmcnt(" #n ")" ::: "memory")
; #define PG8_WAIT_L(n) asm volatile("s_waitcnt lgkmcnt(" #n ")" ::: "memory")
; #define PG8_BAR __builtin_amdgcn_s_barrier()
; #define PG8_SCHED __builtin_amdgcn_sched_barrier(0)
; template <class Epi, class Sched, bool ALIGN_EPI = false, bool SP2 = false>
; __device__ __forceinline__ void gemm_phase(PG8_LAS unsigned char* lds, const Gemm g, const Sched& S, const Epi& E) {
;     ...
;             PG8_WAIT_V(8); PG8_WAIT_L(0); PG8_BAR; PG8_MMA(0, 0, At, B0); PG8_MMA(0, 1, At, B1); PG8_BAR; PG8_SCHED;
;             PG8_LDA(At, 1, 1); PG8_STAGE(PG8_SB(1, 0), b3, voffB); PG8_STAGE(PG8_SB(1, 1), b3 + hstep, voffB); PG8_STAGE(PG8_SA(1, 0), a3, voffA);
;             PG8_WAIT_V(8); PG8_WAIT_L(0); PG8_BAR; PG8_MMA(1, 0, At, B0); PG8_MMA(1, 1, At, B1); PG8_BAR; PG8_SCHED;
	s_setprio 1
	v_mfma_f32_16x16x32_bf16 v[120:123], v[154:157], v[186:189], v[120:123]
	v_mfma_f32_16x16x32_bf16 v[116:119], v[162:165], v[186:189], v[116:119]
	v_mfma_f32_16x16x32_bf16 v[108:111], v[154:157], v[194:197], v[108:111]
	v_mfma_f32_16x16x32_bf16 v[100:103], v[162:165], v[194:197], v[100:103]
	v_mfma_f32_16x16x32_bf16 v[92:95], v[154:157], v[202:205], v[92:95]
	v_mfma_f32_16x16x32_bf16 v[84:87], v[162:165], v[202:205], v[84:87]
	v_mfma_f32_16x16x32_bf16 v[76:79], v[154:157], v[210:213], v[76:79]
	v_mfma_f32_16x16x32_bf16 v[68:71], v[162:165], v[210:213], v[68:71]
	v_mfma_f32_16x16x32_bf16 v[120:123], v[158:161], v[190:193], v[120:123]
	v_mfma_f32_16x16x32_bf16 v[116:119], v[166:169], v[190:193], v[116:119]
	v_mfma_f32_16x16x32_bf16 v[108:111], v[158:161], v[198:201], v[108:111]
	v_mfma_f32_16x16x32_bf16 v[100:103], v[166:169], v[198:201], v[100:103]
	v_mfma_f32_16x16x32_bf16 v[92:95], v[158:161], v[206:209], v[92:95]
	v_mfma_f32_16x16x32_bf16 v[84:87], v[166:169], v[206:209], v[84:87]
	v_mfma_f32_16x16x32_bf16 v[76:79], v[158:161], v[214:217], v[76:79]
	v_mfma_f32_16x16x32_bf16 v[68:71], v[166:169], v[214:217], v[68:71]
	v_mfma_f32_16x16x32_bf16 v[124:127], v[170:173], v[186:189], v[124:127]
	v_mfma_f32_16x16x32_bf16 v[112:115], v[178:181], v[186:189], v[112:115]
	v_mfma_f32_16x16x32_bf16 v[104:107], v[170:173], v[194:197], v[104:107]
	v_mfma_f32_16x16x32_bf16 v[96:99], v[178:181], v[194:197], v[96:99]
	v_mfma_f32_16x16x32_bf16 v[88:91], v[170:173], v[202:205], v[88:91]
	v_mfma_f32_16x16x32_bf16 v[80:83], v[178:181], v[202:205], v[80:83]
	v_mfma_f32_16x16x32_bf16 v[72:75], v[170:173], v[210:213], v[72:75]
	v_mfma_f32_16x16x32_bf16 v[64:67], v[178:181], v[210:213], v[64:67]
	v_mfma_f32_16x16x32_bf16 v[124:127], v[174:177], v[190:193], v[124:127]
	v_mfma_f32_16x16x32_bf16 v[112:115], v[182:185], v[190:193], v[112:115]
	v_mfma_f32_16x16x32_bf16 v[104:107], v[174:177], v[198:201], v[104:107]
	v_mfma_f32_16x16x32_bf16 v[96:99], v[182:185], v[198:201], v[96:99]
	v_mfma_f32_16x16x32_bf16 v[88:91], v[174:177], v[206:209], v[88:91]
	v_mfma_f32_16x16x32_bf16 v[80:83], v[182:185], v[206:209], v[80:83]
	v_mfma_f32_16x16x32_bf16 v[72:75], v[174:177], v[214:217], v[72:75]
	v_mfma_f32_16x16x32_bf16 v[64:67], v[182:185], v[214:217], v[64:67]
	s_barrier
	s_setprio 0
	s_add_i32 s42, s69, s48
	v_lshl_add_u64 v[144:145], v[144:145], 0, s[14:15]
	s_mov_b32 m0, s42
	ds_read_b128 v[186:189], v151 offset:49152
	ds_read_b128 v[190:193], v151 offset:50176
	ds_read_b128 v[194:197], v151 offset:51200
	ds_read_b128 v[198:201], v151 offset:52224
	ds_read_b128 v[202:205], v151 offset:53248
	ds_read_b128 v[206:209], v151 offset:54272
	ds_read_b128 v[210:213], v151 offset:55296
	ds_read_b128 v[214:217], v151 offset:56320
	global_load_lds_dwordx4 v[144:145], off
	s_add_i32 m0, s42, 0x2000
	s_add_u32 s40, s40, 0x40080
	v_lshl_add_u64 v[144:145], v[218:219], 0, s[14:15]
	s_addc_u32 s41, s41, 0
	s_add_i32 s42, s70, s48
	global_load_lds_dwordx4 v[144:145], off
	v_lshl_add_u64 v[144:145], s[40:41], 0, v[132:133]
	s_mov_b32 m0, s42
	s_nop 0
	global_load_lds_dwordx4 v[144:145], off
	v_lshl_add_u64 v[144:145], s[40:41], 0, v[128:129]
	s_add_i32 m0, s42, 0x2000
	s_nop 0
	global_load_lds_dwordx4 v[144:145], off
	v_lshl_add_u64 v[144:145], v[220:221], 0, s[14:15]
	s_mov_b32 m0, s54
	s_nop 0
	global_load_lds_dwordx4 v[144:145], off
	v_lshl_add_u64 v[144:145], v[222:223], 0, s[14:15]
	s_mov_b32 m0, s55
	s_nop 0
	global_load_lds_dwordx4 v[144:145], off
	s_waitcnt vmcnt(8)
	s_waitcnt lgkmcnt(0)
	s_barrier
	s_setprio 1
	v_mfma_f32_16x16x32_bf16 v[60:63], v[154:157], v[186:189], v[60:63]
	v_mfma_f32_16x16x32_bf16 v[52:55], v[162:165], v[186:189], v[52:55]
	v_mfma_f32_16x16x32_bf16 v[44:47], v[154:157], v[194:197], v[44:47]
	v_mfma_f32_16x16x32_bf16 v[36:39], v[162:165], v[194:197], v[36:39]
	v_mfma_f32_16x16x32_bf16 v[28:31], v[154:157], v[202:205], v[28:31]
	v_mfma_f32_16x16x32_bf16 v[20:23], v[162:165], v[202:205], v[20:23]
	v_mfma_f32_16x16x32_bf16 v[12:15], v[154:157], v[210:213], v[12:15]
	v_mfma_f32_16x16x32_bf16 v[4:7], v[162:165], v[210:213], v[4:7]
	v_mfma_f32_16x16x32_bf16 v[60:63], v[158:161], v[190:193], v[60:63]
	v_mfma_f32_16x16x32_bf16 v[52:55], v[166:169], v[190:193], v[52:55]
	v_mfma_f32_16x16x32_bf16 v[44:47], v[158:161], v[198:201], v[44:47]
	v_mfma_f32_16x16x32_bf16 v[36:39], v[166:169], v[198:201], v[36:39]
	v_mfma_f32_16x16x32_bf16 v[28:31], v[158:161], v[206:209], v[28:31]
	v_mfma_f32_16x16x32_bf16 v[20:23], v[166:169], v[206:209], v[20:23]
	v_mfma_f32_16x16x32_bf16 v[12:15], v[158:161], v[214:217], v[12:15]
	v_mfma_f32_16x16x32_bf16 v[4:7], v[166:169], v[214:217], v[4:7]
	v_mfma_f32_16x16x32_bf16 v[56:59], v[170:173], v[186:189], v[56:59]
	v_mfma_f32_16x16x32_bf16 v[48:51], v[178:181], v[186:189], v[48:51]
	v_mfma_f32_16x16x32_bf16 v[40:43], v[170:173], v[194:197], v[40:43]
	v_mfma_f32_16x16x32_bf16 v[32:35], v[178:181], v[194:197], v[32:35]
	v_mfma_f32_16x16x32_bf16 v[24:27], v[170:173], v[202:205], v[24:27]
	v_mfma_f32_16x16x32_bf16 v[16:19], v[178:181], v[202:205], v[16:19]
	v_mfma_f32_16x16x32_bf16 v[8:11], v[170:173], v[210:213], v[8:11]
	v_mfma_f32_16x16x32_bf16 v[0:3], v[178:181], v[210:213], v[0:3]
	v_mfma_f32_16x16x32_bf16 v[56:59], v[174:177], v[190:193], v[56:59]
	v_mfma_f32_16x16x32_bf16 v[48:51], v[182:185], v[190:193], v[48:51]
	v_mfma_f32_16x16x32_bf16 v[40:43], v[174:177], v[198:201], v[40:43]
	v_mfma_f32_16x16x32_bf16 v[32:35], v[182:185], v[198:201], v[32:35]
	v_mfma_f32_16x16x32_bf16 v[24:27], v[174:177], v[206:209], v[24:27]
	v_mfma_f32_16x16x32_bf16 v[16:19], v[182:185], v[206:209], v[16:19]
	v_mfma_f32_16x16x32_bf16 v[8:11], v[174:177], v[214:217], v[8:11]
	v_mfma_f32_16x16x32_bf16 v[0:3], v[182:185], v[214:217], v[0:3]
	s_barrier
	s_setprio 0
	s_add_i32 s68, s68, 2
	s_add_u32 s38, s38, 0x100
	s_addc_u32 s39, s39, 0
	s_add_u32 s66, s66, 0x100
	s_addc_u32 s67, s67, 0

; #define PG8_STAGE(bufoff, gbase, voff) do { _Pragma("unroll") for (int _i = 0; _i < 2; ++_i) \
;         __builtin_amdgcn_global_load_lds((const unsigned*)((const char*)(gbase) + (voff)[_i]), (PG8_LAS unsigned*)(lds + (bufoff) + ldsw + _i * 8192), 16, 0, 0); } while (0)
; #define PG8_LDA(dst, b, h) do { _Pragma("unroll") for (int m = 0; m < 4; ++m) _Pragma("unroll") for (int k = 0; k < 2; ++k) dst[m][k] = *(const PG8_LAS bf16x8*)(lds + PG8_SA(b, h) + aoff + m * 2048 + k * 1024); } while (0)
; #define PG8_LDB(dst, b, h) do { _Pragma("unroll") for (int n = 0; n < 2; ++n) _Pragma("unroll") for (int k = 0; k < 2; ++k) dst[n][k] = *(const PG8_LAS bf16x8*)(lds + PG8_SB(b, h) + boff + n * 2048 + k * 1024); } while (0)
; #define PG8_SCHED __builtin_amdgcn_sched_barrier(0)
; template <class Epi, class Sched, bool ALIGN_EPI = false, bool SP2 = false>
; __device__ __forceinline__ void gemm_phase(PG8_LAS unsigned char* lds, const Gemm g, const Sched& S, const Epi& E) {
;     ...
;         const char* nA = has_next ? (const char*)g.A + (size_t)nxt.pm * tstep : cA; const char* nB = has_next ? (const char*)g.Bt + (size_t)nxt.pn * tstep : cB;
;         for (int t = 0; t < nt; t += 2) {
;             const bool last = (t == nt - 2);
;             if constexpr (Epi::PREFETCH) { if (t == nt - 4) E.prefetch(cur, lds + STAGE_BYTES + 1024, tid); }
;             const char* a1 = cA + (size_t)(t + 1) * kstep;
;             const char* a2 = last ? nA : cA + (size_t)(t + 2) * kstep; const char* b2 = last ? nB : cB + (size_t)(t + 2) * kstep;
;             const char* a3 = a2 + kstep; const char* b3 = b2 + kstep;
;             if (last && has_next) S.a_ready(nxt);
;             if constexpr (SP2) {
;             PG8_LDB(B0, 0, 0); PG8_LDB(B1, 0, 1); PG8_SCHED; PG8_LDA(At, 0, 0); PG8_STAGE(PG8_SA(1, 1), a1 + hstep, voffA);
.LBB0_235:
	s_and_b64 vcc, exec, s[4:5]
	s_cbranch_vccz .Lhoist_skip_0
	s_add_u32 s96, s22, 0x40080
	s_addc_u32 s97, s23, 0
	v_lshl_add_u64 v[144:145], s[96:97], 0, v[136:137]
	s_add_i32 m0, s37, 0xc000
	s_nop 0
	global_load_lds_dwordx4 v[144:145], off
	v_lshl_add_u64 v[144:145], s[96:97], 0, v[138:139]
	s_add_i32 m0, s37, 0xe000
	s_nop 0
	global_load_lds_dwordx4 v[144:145], off

; #define PG8_STAGE(bufoff, gbase, voff) do { _Pragma("unroll") for (int _i = 0; _i < 2; ++_i) \
;         __builtin_amdgcn_global_load_lds((const unsigned*)((const char*)(gbase) + (voff)[_i]), (PG8_LAS unsigned*)(lds + (bufoff) + ldsw + _i * 8192), 16, 0, 0); } while (0)
; #define PG8_WAIT_V(n) asm volatile("s_waitcnt vmcnt(" #n ")" ::: "memory")
; #define PG8_BAR __builtin_amdgcn_s_barrier()
; template <class Epi, class Sched, bool ALIGN_EPI = false, bool SP2 = false>
; __device__ __forceinline__ void gemm_phase(PG8_LAS unsigned char* lds, const Gemm g, const Sched& S, const Epi& E) {
;     const int tid = threadIdx.x, wid = __builtin_amdgcn_readfirstlane(tid >> 6), lane = tid & 63, wr = wid >> 2, wc = wid & 3, fr = lane & 15, fq = lane >> 4;
;     const int K = g.K, nt = K / BK;
;     unsigned voffA[2], voffB[2];
; #pragma unroll
;     for (int i = 0; i < 2; ++i) { int R, C; stage_rc(tid * 16 + i * 8192, R, C); const int Rb = Epi::PERM ? ((R & ~31) + perm32(R & 31)) : R;
;         voffA[i] = (unsigned)(R * K + C) * 2u; voffB[i] = (unsigned)(Rb * K + C) * 2u; }
;     const size_t kstep = (size_t)(BK * 2);
;     const size_t hstep = (size_t)HALF * K * 2;
;     const size_t tstep = 2 * hstep;
;     const unsigned ldsw = (unsigned)wid * 1024u;
;     const int aoff = lds_byte(wr * 64 + fr, fq * 8), boff = lds_byte(wc * 32 + fr, fq * 8);
;     ...
;         PG8_WAIT_V(2); PG8_BAR;
;         PG8_STAGE(PG8_SB(1, 0), cB + kstep, voffB); PG8_STAGE(PG8_SA(1, 0), cA + kstep, voffA); PG8_STAGE(PG8_SB(1, 1), cB + hstep + kstep, voffB);
;         PG8_WAIT_V(6); PG8_BAR;
.LBB0_1188:
	s_mul_i32 s12, s12, s8
	s_sub_i32 s9, s9, s12
	s_sub_i32 s12, s9, s8
	s_cmp_ge_u32 s9, s8
	s_cselect_b32 s9, s12, s9
	s_sub_i32 s12, s9, s8
	s_cmp_ge_u32 s9, s8
	s_cselect_b32 s8, s12, s9
	s_xor_b32 s8, s8, s3
	s_sub_i32 s8, s8, s3
	s_ashr_i32 s9, s8, 31
	s_and_b64 s[12:13], s[30:31], exec
	s_cselect_b32 s12, 25, 28
	s_lshl_b64 s[12:13], s[8:9], s12
	s_add_u32 s15, s4, s12
	s_addc_u32 s19, s5, s13
	s_and_b64 s[12:13], s[30:31], exec
	s_cselect_b32 s12, 12, 15
	s_lshl_b64 s[8:9], s[8:9], s12
	s_mul_hi_u32 s12, s8, 0xffffea00
	s_sub_i32 s12, s12, s8
	s_mulk_i32 s9, 0xea00
	s_add_i32 s12, s12, s9
	s_mulk_i32 s8, 0xea00
	s_add_u32 s8, s15, s8
	s_addc_u32 s9, s19, s12
	s_add_u32 s8, s8, 0xa000000
	s_addc_u32 s9, s9, 0
	s_add_u32 s12, s4, 0x580000
	s_addc_u32 s13, s5, 0
	s_lshl_b32 s4, s14, 5
	s_mov_b64 s[14:15], 0x80
	s_and_b32 s20, s4, 0x60
	s_add_i32 m0, s37, 0x18000
	v_lshl_add_u64 v[6:7], v[6:7], 0, s[14:15]
	s_lshl_b32 s19, s18, 13
	s_lshl_b32 s21, s20, 7
	s_waitcnt vmcnt(2)
	s_barrier
	global_load_lds_dwordx4 v[6:7], off
	v_lshl_add_u64 v[4:5], v[4:5], 0, s[14:15]
	s_add_i32 m0, s37, 0x1a000
	s_add_i32 s53, s37, 0x8000
	s_add_i32 s54, s37, 0xa000
	global_load_lds_dwordx4 v[4:5], off
	v_lshl_add_u64 v[0:1], v[0:1], 0, s[14:15]
	s_mov_b32 m0, s53
	s_add_u32 s4, s40, 0x40080
	global_load_lds_dwordx4 v[0:1], off
	v_lshl_add_u64 v[0:1], v[2:3], 0, s[14:15]
	s_mov_b32 m0, s54
	s_addc_u32 s5, s41, 0
	global_load_lds_dwordx4 v[0:1], off
	s_add_i32 m0, s37, 0x1c000
	v_lshl_add_u64 v[0:1], s[4:5], 0, v[132:133]
	global_load_lds_dwordx4 v[0:1], off
	v_lshl_add_u64 v[0:1], s[4:5], 0, v[128:129]
	s_add_i32 m0, s37, 0x1e000
	v_lshlrev_b32_e32 v2, 2, v242
	global_load_lds_dwordx4 v[0:1], off
	v_and_b32_e32 v0, 15, v242
	v_lshlrev_b32_e32 v1, 1, v11
	v_lshlrev_b32_e32 v3, 6, v242
	s_movk_i32 s4, 0x3c0
	v_lshl_or_b32 v146, s18, 6, v0
	v_lshl_or_b32 v0, v0, 6, v1
	v_and_b32_e32 v2, 32, v2
	v_and_or_b32 v1, v3, s4, v1
	v_bitop3_b32 v147, s21, v1, v2 bitop3:0xf6
	v_lshlrev_b32_e32 v1, 8, v242
	v_bitop3_b32 v0, v0, s19, v2 bitop3:0xde
	v_and_b32_e32 v1, 0x38000, v1
	v_lshlrev_b32_e32 v2, 11, v12
	v_or3_b32 v1, v9, v1, v2
	v_add_u32_e32 v136, v1, v10
	v_lshlrev_b32_e32 v1, 4, v8
	s_waitcnt vmcnt(6)
	s_cmpk_lt_u32 s17, 0x100
	v_and_b32_e32 v1, 0x78000, v1
	s_sext_i32_i16 s63, s16
	s_cselect_b64 s[16:17], -1, 0
	v_or3_b32 v1, v9, v1, v2
	s_add_i32 s57, 0, 0x10000
	s_add_i32 s58, 0, 0x14000
	s_mov_b32 s55, 0
	s_ashr_i32 s56, s61, 31
	v_or_b32_e32 v148, s20, v11
	v_mov_b32_e32 v137, v133
	v_add_u32_e32 v138, v1, v10
	v_mov_b32_e32 v139, v133
	v_mov_b64_e32 v[140:141], 0xb00
	v_mov_b64_e32 v[142:143], 0xaff
	v_add_u32_e32 v149, s57, v147
	v_add_u32_e32 v150, s58, v147
	v_add_u32_e32 v151, 0, v0
	v_mov_b32_e32 v152, 0x358637bd
	s_movk_i32 s59, 0x1600
	s_barrier
	s_mov_b32 s99, 1
	s_branch .LBB0_1191

; #define PG8_STAGE(bufoff, gbase, voff) do { _Pragma("unroll") for (int _i = 0; _i < 2; ++_i) \
;         __builtin_amdgcn_global_load_lds((const unsigned*)((const char*)(gbase) + (voff)[_i]), (PG8_LAS unsigned*)(lds + (bufoff) + ldsw + _i * 8192), 16, 0, 0); } while (0)
; #define PG8_LDA(dst, b, h) do { _Pragma("unroll") for (int m = 0; m < 4; ++m) _Pragma("unroll") for (int k = 0; k < 2; ++k) dst[m][k] = *(const PG8_LAS bf16x8*)(lds + PG8_SA(b, h) + aoff + m * 2048 + k * 1024); } while (0)
; #define PG8_LDB(dst, b, h) do { _Pragma("unroll") for (int n = 0; n < 2; ++n) _Pragma("unroll") for (int k = 0; k < 2; ++k) dst[n][k] = *(const PG8_LAS bf16x8*)(lds + PG8_SB(b, h) + boff + n * 2048 + k * 1024); } while (0)
; #define PG8_WAIT_V(n) asm volatile("s_waitcnt vmcnt(" #n ")" ::: "memory")
; #define PG8_WAIT_L(n) asm volatile("s_waitcnt lgkmcnt(" #n ")" ::: "memory")
; template <class Epi, class Sched, bool ALIGN_EPI = false, bool SP2 = false>
; __device__ __forceinline__ void gemm_phase(PG8_LAS unsigned char* lds, const Gemm g, const Sched& S, const Epi& E) {
;     ...
;         const bool has_next = S.next(ui + 1, nxt);
;         const char* nA = has_next ? (const char*)g.A + (size_t)nxt.pm * tstep : cA; const char* nB = has_next ? (const char*)g.Bt + (size_t)nxt.pn * tstep : cB;
;         for (int t = 0; t < nt; t += 2) {
;             const bool last = (t == nt - 2);
;             if constexpr (Epi::PREFETCH) { if (t == nt - 4) E.prefetch(cur, lds + STAGE_BYTES + 1024, tid); }
;             const char* a1 = cA + (size_t)(t + 1) * kstep;
;             const char* a2 = last ? nA : cA + (size_t)(t + 2) * kstep; const char* b2 = last ? nB : cB + (size_t)(t + 2) * kstep;
;             const char* a3 = a2 + kstep; const char* b3 = b2 + kstep;
;             if (last && has_next) S.a_ready(nxt);
;             if constexpr (SP2) {
;             PG8_LDB(B0, 0, 0); PG8_LDB(B1, 0, 1); PG8_SCHED; PG8_LDA(At, 0, 0); PG8_STAGE(PG8_SA(1, 1), a1 + hstep, voffA);
;             PG8_WAIT_V(8); PG8_WAIT_L(0); PG8_BAR; PG8_MMA(0, 0, At, B0); PG8_MMA(0, 1, At, B1); PG8_BAR; PG8_SCHED;
;             PG8_LDA(At, 0, 1); PG8_STAGE(PG8_SB(0, 0), b2, voffB); PG8_STAGE(PG8_SB(0, 1), b2 + hstep, voffB); PG8_STAGE(PG8_SA(0, 0), a2, voffA);
;             PG8_WAIT_V(8); PG8_WAIT_L(0); PG8_BAR; PG8_MMA(1, 0, At, B0); PG8_MMA(1, 1, At, B1); PG8_BAR; PG8_SCHED;
.LBB0_1193:
	s_ashr_i32 s21, s20, 31
	s_lshl_b64 s[22:23], s[20:21], 19
	s_add_u32 s22, s44, s22
	s_addc_u32 s23, s45, s23
	s_and_b64 s[34:35], s[4:5], exec
	s_cselect_b32 s21, s23, s39
	s_cselect_b32 s64, s22, s38
	s_ashr_i32 s19, s18, 31
	s_lshl_b64 s[34:35], s[18:19], 19
	s_add_u32 s34, s46, s34
	s_addc_u32 s35, s47, s35
	s_and_b64 s[42:43], s[4:5], exec
	s_cselect_b32 s19, s35, s41
	s_cselect_b32 s65, s34, s40
	s_add_u32 s38, s38, 0x40080
	s_addc_u32 s39, s39, 0
	s_add_u32 s66, s40, 0x100
	s_addc_u32 s67, s41, 0
	s_mov_b32 s68, -2
	s_cmp_eq_u32 s99, 0
	s_cbranch_scc1 .Lpeel_hoisted_1
	s_mov_b32 s99, 0
	ds_read_b128 v[154:157], v149
	ds_read_b128 v[158:161], v149 offset:1024
	ds_read_b128 v[162:165], v149 offset:2048
	ds_read_b128 v[166:169], v149 offset:3072
	ds_read_b128 v[170:173], v150
	ds_read_b128 v[174:177], v150 offset:1024
	ds_read_b128 v[178:181], v150 offset:2048
	ds_read_b128 v[182:185], v150 offset:3072
	s_add_u32 s40, s38, 0xfffc0080
	s_addc_u32 s41, s39, -1
	s_cmp_eq_u32 s68, 12
	s_cselect_b32 s43, s21, s41
	s_cselect_b32 s42, s64, s40
	s_cselect_b32 s41, s19, s67
	s_cselect_b32 s40, s65, s66
	v_lshl_add_u64 v[144:145], s[38:39], 0, v[136:137]
	s_add_i32 m0, s37, 0xc000
	ds_read_b128 v[186:189], v151
	ds_read_b128 v[190:193], v151 offset:1024
	ds_read_b128 v[194:197], v151 offset:2048
	ds_read_b128 v[198:201], v151 offset:3072
	ds_read_b128 v[202:205], v151 offset:4096
	ds_read_b128 v[206:209], v151 offset:5120
	ds_read_b128 v[210:213], v151 offset:6144
	ds_read_b128 v[214:217], v151 offset:7168
	global_load_lds_dwordx4 v[144:145], off
	v_lshl_add_u64 v[144:145], s[38:39], 0, v[138:139]
	s_add_i32 m0, s37, 0xe000
	s_nop 0
	global_load_lds_dwordx4 v[144:145], off
	s_waitcnt vmcnt(8)
	s_waitcnt lgkmcnt(0)
	s_barrier
	s_setprio 1
	v_mfma_f32_16x16x32_bf16 v[120:123], v[154:157], v[186:189], 0
	v_mfma_f32_16x16x32_bf16 v[116:119], v[162:165], v[186:189], 0
	v_mfma_f32_16x16x32_bf16 v[108:111], v[154:157], v[194:197], 0
	v_mfma_f32_16x16x32_bf16 v[100:103], v[162:165], v[194:197], 0
	v_mfma_f32_16x16x32_bf16 v[92:95], v[154:157], v[202:205], 0
	v_mfma_f32_16x16x32_bf16 v[84:87], v[162:165], v[202:205], 0
	v_mfma_f32_16x16x32_bf16 v[76:79], v[154:157], v[210:213], 0
	v_mfma_f32_16x16x32_bf16 v[68:71], v[162:165], v[210:213], 0
	v_mfma_f32_16x16x32_bf16 v[120:123], v[158:161], v[190:193], v[120:123]
	v_mfma_f32_16x16x32_bf16 v[116:119], v[166:169], v[190:193], v[116:119]
	v_mfma_f32_16x16x32_bf16 v[108:111], v[158:161], v[198:201], v[108:111]
	v_mfma_f32_16x16x32_bf16 v[100:103], v[166:169], v[198:201], v[100:103]
	v_mfma_f32_16x16x32_bf16 v[92:95], v[158:161], v[206:209], v[92:95]
	v_mfma_f32_16x16x32_bf16 v[84:87], v[166:169], v[206:209], v[84:87]
	v_mfma_f32_16x16x32_bf16 v[76:79], v[158:161], v[214:217], v[76:79]
	v_mfma_f32_16x16x32_bf16 v[68:71], v[166:169], v[214:217], v[68:71]
	v_mfma_f32_16x16x32_bf16 v[124:127], v[170:173], v[186:189], 0
	v_mfma_f32_16x16x32_bf16 v[112:115], v[178:181], v[186:189], 0
	v_mfma_f32_16x16x32_bf16 v[104:107], v[170:173], v[194:197], 0
	v_mfma_f32_16x16x32_bf16 v[96:99], v[178:181], v[194:197], 0
	v_mfma_f32_16x16x32_bf16 v[88:91], v[170:173], v[202:205], 0
	v_mfma_f32_16x16x32_bf16 v[80:83], v[178:181], v[202:205], 0
	v_mfma_f32_16x16x32_bf16 v[72:75], v[170:173], v[210:213], 0
	v_mfma_f32_16x16x32_bf16 v[64:67], v[178:181], v[210:213], 0
	v_mfma_f32_16x16x32_bf16 v[124:127], v[174:177], v[190:193], v[124:127]
	v_mfma_f32_16x16x32_bf16 v[112:115], v[182:185], v[190:193], v[112:115]
	v_mfma_f32_16x16x32_bf16 v[104:107], v[174:177], v[198:201], v[104:107]
	v_mfma_f32_16x16x32_bf16 v[96:99], v[182:185], v[198:201], v[96:99]
	v_mfma_f32_16x16x32_bf16 v[88:91], v[174:177], v[206:209], v[88:91]
	v_mfma_f32_16x16x32_bf16 v[80:83], v[182:185], v[206:209], v[80:83]
	v_mfma_f32_16x16x32_bf16 v[72:75], v[174:177], v[214:217], v[72:75]
	v_mfma_f32_16x16x32_bf16 v[64:67], v[182:185], v[214:217], v[64:67]
	s_barrier
	s_setprio 0
	s_add_i32 s69, s57, s48
	v_lshl_add_u64 v[144:145], s[40:41], 0, v[132:133]
	s_mov_b32 m0, s69
	ds_read_b128 v[186:189], v151 offset:16384
	ds_read_b128 v[190:193], v151 offset:17408
	ds_read_b128 v[194:197], v151 offset:18432
	ds_read_b128 v[198:201], v151 offset:19456
	ds_read_b128 v[202:205], v151 offset:20480
	ds_read_b128 v[206:209], v151 offset:21504
	ds_read_b128 v[210:213], v151 offset:22528
	ds_read_b128 v[214:217], v151 offset:23552
	global_load_lds_dwordx4 v[144:145], off
	s_add_i32 m0, s69, 0x2000
	s_add_u32 s70, s40, 0x40000
	v_lshl_add_u64 v[218:219], s[40:41], 0, v[128:129]
	s_addc_u32 s71, s41, 0
	s_add_i32 s69, s58, s48
	global_load_lds_dwordx4 v[218:219], off
	v_lshl_add_u64 v[220:221], s[70:71], 0, v[132:133]
	s_mov_b32 m0, s69
	v_lshl_add_u64 v[222:223], s[42:43], 0, v[130:131]
	global_load_lds_dwordx4 v[220:221], off
	v_lshl_add_u64 v[220:221], s[70:71], 0, v[128:129]
	s_add_i32 m0, s69, 0x2000
	s_nop 0
	global_load_lds_dwordx4 v[220:221], off
	v_lshl_add_u64 v[220:221], s[42:43], 0, v[134:135]
	s_mov_b32 m0, s37
	s_nop 0
	global_load_lds_dwordx4 v[220:221], off
	s_mov_b32 m0, s50
	s_nop 0
	global_load_lds_dwordx4 v[222:223], off
	s_waitcnt vmcnt(8)
	s_waitcnt lgkmcnt(0)
	s_barrier
; #define PG8_STAGE(bufoff, gbase, voff) do { _Pragma("unroll") for (int _i = 0; _i < 2; ++_i) \
;         __builtin_amdgcn_global_load_lds((const unsigned*)((const char*)(gbase) + (voff)[_i]), (PG8_LAS unsigned*)(lds + (bufoff) + ldsw + _i * 8192), 16, 0, 0); } while (0)
; #define PG8_LDA(dst, b, h) do { _Pragma("unroll") for (int m = 0; m < 4; ++m) _Pragma("unroll") for (int k = 0; k < 2; ++k) dst[m][k] = *(const PG8_LAS bf16x8*)(lds + PG8_SA(b, h) + aoff + m * 2048 + k * 1024); } while (0)
; #define PG8_LDB(dst, b, h) do { _Pragma("unroll") for (int n = 0; n < 2; ++n) _Pragma("unroll") for (int k = 0; k < 2; ++k) dst[n][k] = *(const PG8_LAS bf16x8*)(lds + PG8_SB(b, h) + boff + n * 2048 + k * 1024); } while (0)
; #define PG8_MMA(ai, bj, At, Bt) do { __builtin_amdgcn_s_setprio(1); _Pragma("unroll") for (int m = 0; m < 4; ++m) _Pragma("unroll") for (int n = 0; n < 2; ++n) _Pragma("unroll") for (int k = 0; k < 2; ++k) \
;         acc[ai][bj][m][n] = __builtin_amdgcn_mfma_f32_16x16x32_bf16(Bt[n][k], At[m][k], acc[ai][bj][m][n], 0, 0, 0); __builtin_amdgcn_s_setprio(0); } while (0)
; #define PG8_WAIT_V(n) asm volatile("s_waitcnt vmcnt(" #n ")" ::: "memory")
; #define PG8_WAIT_L(n) asm volatile("s_waitcnt lgkmcnt(" #n ")" ::: "memory")
; #define PG8_BAR __builtin_amdgcn_s_barrier()
; #define PG8_SCHED __builtin_amdgcn_sched_barrier(0)
; template <class Epi, class Sched, bool ALIGN_EPI = false, bool SP2 = false>
; __device__ __forceinline__ void gemm_phase(PG8_LAS unsigned char* lds, const Gemm g, const Sched& S, const Epi& E) {
;     ...
;             PG8_WAIT_V(8); PG8_WAIT_L(0); PG8_BAR; PG8_MMA(0, 0, At, B0); PG8_MMA(0, 1, At, B1); PG8_BAR; PG8_SCHED;
;             PG8_LDA(At, 0, 1); PG8_STAGE(PG8_SB(0, 0), b2, voffB); PG8_STAGE(PG8_SB(0, 1), b2 + hstep, voffB); PG8_STAGE(PG8_SA(0, 0), a2, voffA);
;             PG8_WAIT_V(8); PG8_WAIT_L(0); PG8_BAR; PG8_MMA(1, 0, At, B0); PG8_MMA(1, 1, At, B1); PG8_BAR; PG8_SCHED;
;             PG8_LDB(B0, 1, 0); PG8_LDB(B1, 1, 1); PG8_SCHED; PG8_LDA(At, 1, 0); PG8_STAGE(PG8_SA(0, 1), a2 + hstep, voffA);
;             PG8_WAIT_V(8); PG8_WAIT_L(0); PG8_BAR; PG8_MMA(0, 0, At, B0); PG8_MMA(0, 1, At, B1); PG8_BAR; PG8_SCHED;
	s_setprio 1
	v_mfma_f32_16x16x32_bf16 v[60:63], v[154:157], v[186:189], 0
	v_mfma_f32_16x16x32_bf16 v[52:55], v[162:165], v[186:189], 0
	v_mfma_f32_16x16x32_bf16 v[44:47], v[154:157], v[194:197], 0
	v_mfma_f32_16x16x32_bf16 v[36:39], v[162:165], v[194:197], 0
	v_mfma_f32_16x16x32_bf16 v[28:31], v[154:157], v[202:205], 0
	v_mfma_f32_16x16x32_bf16 v[20:23], v[162:165], v[202:205], 0
	v_mfma_f32_16x16x32_bf16 v[12:15], v[154:157], v[210:213], 0
	v_mfma_f32_16x16x32_bf16 v[4:7], v[162:165], v[210:213], 0
	v_mfma_f32_16x16x32_bf16 v[60:63], v[158:161], v[190:193], v[60:63]
	v_mfma_f32_16x16x32_bf16 v[52:55], v[166:169], v[190:193], v[52:55]
	v_mfma_f32_16x16x32_bf16 v[44:47], v[158:161], v[198:201], v[44:47]
	v_mfma_f32_16x16x32_bf16 v[36:39], v[166:169], v[198:201], v[36:39]
	v_mfma_f32_16x16x32_bf16 v[28:31], v[158:161], v[206:209], v[28:31]
	v_mfma_f32_16x16x32_bf16 v[20:23], v[166:169], v[206:209], v[20:23]
	v_mfma_f32_16x16x32_bf16 v[12:15], v[158:161], v[214:217], v[12:15]
	v_mfma_f32_16x16x32_bf16 v[4:7], v[166:169], v[214:217], v[4:7]
	v_mfma_f32_16x16x32_bf16 v[56:59], v[170:173], v[186:189], 0
	v_mfma_f32_16x16x32_bf16 v[48:51], v[178:181], v[186:189], 0
	v_mfma_f32_16x16x32_bf16 v[40:43], v[170:173], v[194:197], 0
	v_mfma_f32_16x16x32_bf16 v[32:35], v[178:181], v[194:197], 0
	v_mfma_f32_16x16x32_bf16 v[24:27], v[170:173], v[202:205], 0
	v_mfma_f32_16x16x32_bf16 v[16:19], v[178:181], v[202:205], 0
	v_mfma_f32_16x16x32_bf16 v[8:11], v[170:173], v[210:213], 0
	v_mfma_f32_16x16x32_bf16 v[0:3], v[178:181], v[210:213], 0
	v_mfma_f32_16x16x32_bf16 v[56:59], v[174:177], v[190:193], v[56:59]
	v_mfma_f32_16x16x32_bf16 v[48:51], v[182:185], v[190:193], v[48:51]
	v_mfma_f32_16x16x32_bf16 v[40:43], v[174:177], v[198:201], v[40:43]
	v_mfma_f32_16x16x32_bf16 v[32:35], v[182:185], v[198:201], v[32:35]
	v_mfma_f32_16x16x32_bf16 v[24:27], v[174:177], v[206:209], v[24:27]
	v_mfma_f32_16x16x32_bf16 v[16:19], v[182:185], v[206:209], v[16:19]
	v_mfma_f32_16x16x32_bf16 v[8:11], v[174:177], v[214:217], v[8:11]
	v_mfma_f32_16x16x32_bf16 v[0:3], v[182:185], v[214:217], v[0:3]
	s_barrier
	s_setprio 0
	s_add_i32 s69, 0, 0x18000
	v_add_u32_e32 v153, s69, v147
	s_add_i32 s70, 0, 0x1c000
	ds_read_b128 v[154:157], v153
	ds_read_b128 v[158:161], v153 offset:1024
	ds_read_b128 v[162:165], v153 offset:2048
	ds_read_b128 v[166:169], v153 offset:3072
	v_add_u32_e32 v153, s70, v147
	ds_read_b128 v[170:173], v153
	ds_read_b128 v[174:177], v153 offset:1024
	ds_read_b128 v[178:181], v153 offset:2048
	ds_read_b128 v[182:185], v153 offset:3072
	s_add_u32 s42, s42, 0x40000
	s_addc_u32 s43, s43, 0
	s_mov_b32 m0, s51
	v_lshl_add_u64 v[224:225], s[42:43], 0, v[134:135]
	ds_read_b128 v[186:189], v151 offset:32768
	ds_read_b128 v[190:193], v151 offset:33792
	ds_read_b128 v[194:197], v151 offset:34816
	ds_read_b128 v[198:201], v151 offset:35840
	ds_read_b128 v[202:205], v151 offset:36864
	ds_read_b128 v[206:209], v151 offset:37888
	ds_read_b128 v[210:213], v151 offset:38912
	ds_read_b128 v[214:217], v151 offset:39936
	global_load_lds_dwordx4 v[224:225], off
	v_lshl_add_u64 v[224:225], s[42:43], 0, v[130:131]
	s_mov_b32 m0, s52
	s_nop 0
	global_load_lds_dwordx4 v[224:225], off
	s_waitcnt vmcnt(8)
	s_waitcnt lgkmcnt(0)
	s_barrier
	s_setprio 1
	v_mfma_f32_16x16x32_bf16 v[120:123], v[154:157], v[186:189], v[120:123]
	v_mfma_f32_16x16x32_bf16 v[116:119], v[162:165], v[186:189], v[116:119]
	v_mfma_f32_16x16x32_bf16 v[108:111], v[154:157], v[194:197], v[108:111]
	v_mfma_f32_16x16x32_bf16 v[100:103], v[162:165], v[194:197], v[100:103]
	v_mfma_f32_16x16x32_bf16 v[92:95], v[154:157], v[202:205], v[92:95]
	v_mfma_f32_16x16x32_bf16 v[84:87], v[162:165], v[202:205], v[84:87]
	v_mfma_f32_16x16x32_bf16 v[76:79], v[154:157], v[210:213], v[76:79]
	v_mfma_f32_16x16x32_bf16 v[68:71], v[162:165], v[210:213], v[68:71]
	v_mfma_f32_16x16x32_bf16 v[120:123], v[158:161], v[190:193], v[120:123]
	v_mfma_f32_16x16x32_bf16 v[116:119], v[166:169], v[190:193], v[116:119]
	v_mfma_f32_16x16x32_bf16 v[108:111], v[158:161], v[198:201], v[108:111]
	v_mfma_f32_16x16x32_bf16 v[100:103], v[166:169], v[198:201], v[100:103]
	v_mfma_f32_16x16x32_bf16 v[92:95], v[158:161], v[206:209], v[92:95]
	v_mfma_f32_16x16x32_bf16 v[84:87], v[166:169], v[206:209], v[84:87]
	v_mfma_f32_16x16x32_bf16 v[76:79], v[158:161], v[214:217], v[76:79]
	v_mfma_f32_16x16x32_bf16 v[68:71], v[166:169], v[214:217], v[68:71]
	v_mfma_f32_16x16x32_bf16 v[124:127], v[170:173], v[186:189], v[124:127]
	v_mfma_f32_16x16x32_bf16 v[112:115], v[178:181], v[186:189], v[112:115]
	v_mfma_f32_16x16x32_bf16 v[104:107], v[170:173], v[194:197], v[104:107]
	v_mfma_f32_16x16x32_bf16 v[96:99], v[178:181], v[194:197], v[96:99]
	v_mfma_f32_16x16x32_bf16 v[88:91], v[170:173], v[202:205], v[88:91]
	v_mfma_f32_16x16x32_bf16 v[80:83], v[178:181], v[202:205], v[80:83]
	v_mfma_f32_16x16x32_bf16 v[72:75], v[170:173], v[210:213], v[72:75]
	v_mfma_f32_16x16x32_bf16 v[64:67], v[178:181], v[210:213], v[64:67]
	v_mfma_f32_16x16x32_bf16 v[124:127], v[174:177], v[190:193], v[124:127]
	v_mfma_f32_16x16x32_bf16 v[112:115], v[182:185], v[190:193], v[112:115]
	v_mfma_f32_16x16x32_bf16 v[104:107], v[174:177], v[198:201], v[104:107]
	v_mfma_f32_16x16x32_bf16 v[96:99], v[182:185], v[198:201], v[96:99]
	v_mfma_f32_16x16x32_bf16 v[88:91], v[174:177], v[206:209], v[88:91]
	v_mfma_f32_16x16x32_bf16 v[80:83], v[182:185], v[206:209], v[80:83]
	v_mfma_f32_16x16x32_bf16 v[72:75], v[174:177], v[214:217], v[72:75]
	v_mfma_f32_16x16x32_bf16 v[64:67], v[182:185], v[214:217], v[64:67]
	s_barrier
; #define PG8_STAGE(bufoff, gbase, voff) do { _Pragma("unroll") for (int _i = 0; _i < 2; ++_i) \
;         __builtin_amdgcn_global_load_lds((const unsigned*)((const char*)(gbase) + (voff)[_i]), (PG8_LAS unsigned*)(lds + (bufoff) + ldsw + _i * 8192), 16, 0, 0); } while (0)
; #define PG8_LDA(dst, b, h) do { _Pragma("unroll") for (int m = 0; m < 4; ++m) _Pragma("unroll") for (int k = 0; k < 2; ++k) dst[m][k] = *(const PG8_LAS bf16x8*)(lds + PG8_SA(b, h) + aoff + m * 2048 + k * 1024); } while (0)
; #define PG8_LDB(dst, b, h) do { _Pragma("unroll") for (int n = 0; n < 2; ++n) _Pragma("unroll") for (int k = 0; k < 2; ++k) dst[n][k] = *(const PG8_LAS bf16x8*)(lds + PG8_SB(b, h) + boff + n * 2048 + k * 1024); } while (0)
; #define PG8_MMA(ai, bj, At, Bt) do { __builtin_amdgcn_s_setprio(1); _Pragma("unroll") for (int m = 0; m < 4; ++m) _Pragma("unroll") for (int n = 0; n < 2; ++n) _Pragma("unroll") for (int k = 0; k < 2; ++k) \
;         acc[ai][bj][m][n] = __builtin_amdgcn_mfma_f32_16x16x32_bf16(Bt[n][k], At[m][k], acc[ai][bj][m][n], 0, 0, 0); __builtin_amdgcn_s_setprio(0); } while (0)
; #define PG8_WAIT_V(n) asm volatile("s_waitcnt vmcnt(" #n ")" ::: "memory")
; #define PG8_WAIT_L(n) asm volatile("s_waitcnt lgkmcnt(" #n ")" ::: "memory")
; #define PG8_BAR __builtin_amdgcn_s_barrier()
; #define PG8_SCHED __builtin_amdgcn_sched_barrier(0)
; template <class Epi, class Sched, bool ALIGN_EPI = false, bool SP2 = false>
; __device__ __forceinline__ void gemm_phase(PG8_LAS unsigned char* lds, const Gemm g, const Sched& S, const Epi& E) {
;     ...
;             PG8_LDB(B0, 0, 0); PG8_LDB(B1, 0, 1); PG8_SCHED; PG8_LDA(At, 0, 0); PG8_STAGE(PG8_SA(1, 1), a1 + hstep, voffA);
;             PG8_WAIT_V(8); PG8_WAIT_L(0); PG8_BAR; PG8_MMA(0, 0, At, B0); PG8_MMA(0, 1, At, B1); PG8_BAR; PG8_SCHED;
;     ...
;             PG8_LDA(At, 1, 1); PG8_STAGE(PG8_SB(1, 0), b3, voffB); PG8_STAGE(PG8_SB(1, 1), b3 + hstep, voffB); PG8_STAGE(PG8_SA(1, 0), a3, voffA);
;             PG8_WAIT_V(8); PG8_WAIT_L(0); PG8_BAR; PG8_MMA(1, 0, At, B0); PG8_MMA(1, 1, At, B1); PG8_BAR; PG8_SCHED;
	s_setprio 0
	s_add_i32 s42, s69, s48
	v_lshl_add_u64 v[144:145], v[144:145], 0, s[14:15]
	s_mov_b32 m0, s42
	ds_read_b128 v[186:189], v151 offset:49152
	ds_read_b128 v[190:193], v151 offset:50176
	ds_read_b128 v[194:197], v151 offset:51200
	ds_read_b128 v[198:201], v151 offset:52224
	ds_read_b128 v[202:205], v151 offset:53248
	ds_read_b128 v[206:209], v151 offset:54272
	ds_read_b128 v[210:213], v151 offset:55296
	ds_read_b128 v[214:217], v151 offset:56320
	global_load_lds_dwordx4 v[144:145], off
	s_add_i32 m0, s42, 0x2000
	s_add_u32 s40, s40, 0x40080
	v_lshl_add_u64 v[144:145], v[218:219], 0, s[14:15]
	s_addc_u32 s41, s41, 0
	s_add_i32 s42, s70, s48
	global_load_lds_dwordx4 v[144:145], off
	v_lshl_add_u64 v[144:145], s[40:41], 0, v[132:133]
	s_mov_b32 m0, s42
	s_nop 0
	global_load_lds_dwordx4 v[144:145], off
	v_lshl_add_u64 v[144:145], s[40:41], 0, v[128:129]
	s_add_i32 m0, s42, 0x2000
	s_nop 0
	global_load_lds_dwordx4 v[144:145], off
	v_lshl_add_u64 v[144:145], v[220:221], 0, s[14:15]
	s_mov_b32 m0, s53
	s_nop 0
	global_load_lds_dwordx4 v[144:145], off
	v_lshl_add_u64 v[144:145], v[222:223], 0, s[14:15]
	s_mov_b32 m0, s54
	s_nop 0
	global_load_lds_dwordx4 v[144:145], off
	s_waitcnt vmcnt(8)
	s_waitcnt lgkmcnt(0)
	s_barrier
	s_setprio 1
	v_mfma_f32_16x16x32_bf16 v[60:63], v[154:157], v[186:189], v[60:63]
	v_mfma_f32_16x16x32_bf16 v[52:55], v[162:165], v[186:189], v[52:55]
	v_mfma_f32_16x16x32_bf16 v[44:47], v[154:157], v[194:197], v[44:47]
	v_mfma_f32_16x16x32_bf16 v[36:39], v[162:165], v[194:197], v[36:39]
	v_mfma_f32_16x16x32_bf16 v[28:31], v[154:157], v[202:205], v[28:31]
	v_mfma_f32_16x16x32_bf16 v[20:23], v[162:165], v[202:205], v[20:23]
	v_mfma_f32_16x16x32_bf16 v[12:15], v[154:157], v[210:213], v[12:15]
	v_mfma_f32_16x16x32_bf16 v[4:7], v[162:165], v[210:213], v[4:7]
	v_mfma_f32_16x16x32_bf16 v[60:63], v[158:161], v[190:193], v[60:63]
	v_mfma_f32_16x16x32_bf16 v[52:55], v[166:169], v[190:193], v[52:55]
	v_mfma_f32_16x16x32_bf16 v[44:47], v[158:161], v[198:201], v[44:47]
	v_mfma_f32_16x16x32_bf16 v[36:39], v[166:169], v[198:201], v[36:39]
	v_mfma_f32_16x16x32_bf16 v[28:31], v[158:161], v[206:209], v[28:31]
	v_mfma_f32_16x16x32_bf16 v[20:23], v[166:169], v[206:209], v[20:23]
	v_mfma_f32_16x16x32_bf16 v[12:15], v[158:161], v[214:217], v[12:15]
	v_mfma_f32_16x16x32_bf16 v[4:7], v[166:169], v[214:217], v[4:7]
	v_mfma_f32_16x16x32_bf16 v[56:59], v[170:173], v[186:189], v[56:59]
	v_mfma_f32_16x16x32_bf16 v[48:51], v[178:181], v[186:189], v[48:51]
	v_mfma_f32_16x16x32_bf16 v[40:43], v[170:173], v[194:197], v[40:43]
	v_mfma_f32_16x16x32_bf16 v[32:35], v[178:181], v[194:197], v[32:35]
	v_mfma_f32_16x16x32_bf16 v[24:27], v[170:173], v[202:205], v[24:27]
	v_mfma_f32_16x16x32_bf16 v[16:19], v[178:181], v[202:205], v[16:19]
	v_mfma_f32_16x16x32_bf16 v[8:11], v[170:173], v[210:213], v[8:11]
	v_mfma_f32_16x16x32_bf16 v[0:3], v[178:181], v[210:213], v[0:3]
	v_mfma_f32_16x16x32_bf16 v[56:59], v[174:177], v[190:193], v[56:59]
	v_mfma_f32_16x16x32_bf16 v[48:51], v[182:185], v[190:193], v[48:51]
	v_mfma_f32_16x16x32_bf16 v[40:43], v[174:177], v[198:201], v[40:43]
	v_mfma_f32_16x16x32_bf16 v[32:35], v[182:185], v[198:201], v[32:35]
	v_mfma_f32_16x16x32_bf16 v[24:27], v[174:177], v[206:209], v[24:27]
	v_mfma_f32_16x16x32_bf16 v[16:19], v[182:185], v[206:209], v[16:19]
	v_mfma_f32_16x16x32_bf16 v[8:11], v[174:177], v[214:217], v[8:11]
	v_mfma_f32_16x16x32_bf16 v[0:3], v[182:185], v[214:217], v[0:3]
	s_barrier
	s_setprio 0
	s_add_i32 s68, s68, 2
	s_add_u32 s38, s38, 0x100
	s_addc_u32 s39, s39, 0
	s_add_u32 s66, s66, 0x100
	s_addc_u32 s67, s67, 0
	s_branch .LBB0_1194
.Lpeel_hoisted_1:
	ds_read_b128 v[154:157], v149
	ds_read_b128 v[158:161], v149 offset:1024
	ds_read_b128 v[162:165], v149 offset:2048
	ds_read_b128 v[166:169], v149 offset:3072
	ds_read_b128 v[170:173], v150
	ds_read_b128 v[174:177], v150 offset:1024
	ds_read_b128 v[178:181], v150 offset:2048
	ds_read_b128 v[182:185], v150 offset:3072
	s_add_u32 s40, s38, 0xfffc0080
	s_addc_u32 s41, s39, -1
	s_cmp_eq_u32 s68, 12
	s_cselect_b32 s43, s21, s41
	s_cselect_b32 s42, s64, s40
	s_cselect_b32 s41, s19, s67
	s_cselect_b32 s40, s65, s66
	ds_read_b128 v[186:189], v151
	ds_read_b128 v[190:193], v151 offset:1024
	ds_read_b128 v[194:197], v151 offset:2048
	ds_read_b128 v[198:201], v151 offset:3072
	ds_read_b128 v[202:205], v151 offset:4096
	ds_read_b128 v[206:209], v151 offset:5120
	ds_read_b128 v[210:213], v151 offset:6144
	ds_read_b128 v[214:217], v151 offset:7168
	s_waitcnt vmcnt(8)
	s_waitcnt lgkmcnt(0)
	s_barrier
	s_setprio 1
	v_mfma_f32_16x16x32_bf16 v[120:123], v[154:157], v[186:189], 0
	v_mfma_f32_16x16x32_bf16 v[116:119], v[162:165], v[186:189], 0
	v_mfma_f32_16x16x32_bf16 v[108:111], v[154:157], v[194:197], 0
	v_mfma_f32_16x16x32_bf16 v[100:103], v[162:165], v[194:197], 0
	v_mfma_f32_16x16x32_bf16 v[92:95], v[154:157], v[202:205], 0
	v_mfma_f32_16x16x32_bf16 v[84:87], v[162:165], v[202:205], 0
	v_mfma_f32_16x16x32_bf16 v[76:79], v[154:157], v[210:213], 0
	v_mfma_f32_16x16x32_bf16 v[68:71], v[162:165], v[210:213], 0
	v_mfma_f32_16x16x32_bf16 v[120:123], v[158:161], v[190:193], v[120:123]
	v_mfma_f32_16x16x32_bf16 v[116:119], v[166:169], v[190:193], v[116:119]
	v_mfma_f32_16x16x32_bf16 v[108:111], v[158:161], v[198:201], v[108:111]
	v_mfma_f32_16x16x32_bf16 v[100:103], v[166:169], v[198:201], v[100:103]
	v_mfma_f32_16x16x32_bf16 v[92:95], v[158:161], v[206:209], v[92:95]
	v_mfma_f32_16x16x32_bf16 v[84:87], v[166:169], v[206:209], v[84:87]
	v_mfma_f32_16x16x32_bf16 v[76:79], v[158:161], v[214:217], v[76:79]
	v_mfma_f32_16x16x32_bf16 v[68:71], v[166:169], v[214:217], v[68:71]
	v_mfma_f32_16x16x32_bf16 v[124:127], v[170:173], v[186:189], 0
	v_mfma_f32_16x16x32_bf16 v[112:115], v[178:181], v[186:189], 0
	v_mfma_f32_16x16x32_bf16 v[104:107], v[170:173], v[194:197], 0
	v_mfma_f32_16x16x32_bf16 v[96:99], v[178:181], v[194:197], 0
	v_mfma_f32_16x16x32_bf16 v[88:91], v[170:173], v[202:205], 0
	v_mfma_f32_16x16x32_bf16 v[80:83], v[178:181], v[202:205], 0
	v_mfma_f32_16x16x32_bf16 v[72:75], v[170:173], v[210:213], 0
	v_mfma_f32_16x16x32_bf16 v[64:67], v[178:181], v[210:213], 0
	v_mfma_f32_16x16x32_bf16 v[124:127], v[174:177], v[190:193], v[124:127]
	v_mfma_f32_16x16x32_bf16 v[112:115], v[182:185], v[190:193], v[112:115]
	v_mfma_f32_16x16x32_bf16 v[104:107], v[174:177], v[198:201], v[104:107]
	v_mfma_f32_16x16x32_bf16 v[96:99], v[182:185], v[198:201], v[96:99]
	v_mfma_f32_16x16x32_bf16 v[88:91], v[174:177], v[206:209], v[88:91]
	v_mfma_f32_16x16x32_bf16 v[80:83], v[182:185], v[206:209], v[80:83]
	v_mfma_f32_16x16x32_bf16 v[72:75], v[174:177], v[214:217], v[72:75]
	v_mfma_f32_16x16x32_bf16 v[64:67], v[182:185], v[214:217], v[64:67]
	s_barrier
; #define PG8_STAGE(bufoff, gbase, voff) do { _Pragma("unroll") for (int _i = 0; _i < 2; ++_i) \
;         __builtin_amdgcn_global_load_lds((const unsigned*)((const char*)(gbase) + (voff)[_i]), (PG8_LAS unsigned*)(lds + (bufoff) + ldsw + _i * 8192), 16, 0, 0); } while (0)
; #define PG8_LDA(dst, b, h) do { _Pragma("unroll") for (int m = 0; m < 4; ++m) _Pragma("unroll") for (int k = 0; k < 2; ++k) dst[m][k] = *(const PG8_LAS bf16x8*)(lds + PG8_SA(b, h) + aoff + m * 2048 + k * 1024); } while (0)
; #define PG8_LDB(dst, b, h) do { _Pragma("unroll") for (int n = 0; n < 2; ++n) _Pragma("unroll") for (int k = 0; k < 2; ++k) dst[n][k] = *(const PG8_LAS bf16x8*)(lds + PG8_SB(b, h) + boff + n * 2048 + k * 1024); } while (0)
; #define PG8_MMA(ai, bj, At, Bt) do { __builtin_amdgcn_s_setprio(1); _Pragma("unroll") for (int m = 0; m < 4; ++m) _Pragma("unroll") for (int n = 0; n < 2; ++n) _Pragma("unroll") for (int k = 0; k < 2; ++k) \
;         acc[ai][bj][m][n] = __builtin_amdgcn_mfma_f32_16x16x32_bf16(Bt[n][k], At[m][k], acc[ai][bj][m][n], 0, 0, 0); __builtin_amdgcn_s_setprio(0); } while (0)
; #define PG8_WAIT_V(n) asm volatile("s_waitcnt vmcnt(" #n ")" ::: "memory")
; #define PG8_WAIT_L(n) asm volatile("s_waitcnt lgkmcnt(" #n ")" ::: "memory")
; #define PG8_BAR __builtin_amdgcn_s_barrier()
; #define PG8_SCHED __builtin_amdgcn_sched_barrier(0)
; template <class Epi, class Sched, bool ALIGN_EPI = false, bool SP2 = false>
; __device__ __forceinline__ void gemm_phase(PG8_LAS unsigned char* lds, const Gemm g, const Sched& S, const Epi& E) {
;     ...
;             PG8_LDA(At, 0, 1); PG8_STAGE(PG8_SB(0, 0), b2, voffB); PG8_STAGE(PG8_SB(0, 1), b2 + hstep, voffB); PG8_STAGE(PG8_SA(0, 0), a2, voffA);
;             PG8_WAIT_V(8); PG8_WAIT_L(0); PG8_BAR; PG8_MMA(1, 0, At, B0); PG8_MMA(1, 1, At, B1); PG8_BAR; PG8_SCHED;
;             PG8_LDB(B0, 1, 0); PG8_LDB(B1, 1, 1); PG8_SCHED; PG8_LDA(At, 1, 0); PG8_STAGE(PG8_SA(0, 1), a2 + hstep, voffA);
;             PG8_WAIT_V(8); PG8_WAIT_L(0); PG8_BAR; PG8_MMA(0, 0, At, B0); PG8_MMA(0, 1, At, B1); PG8_BAR; PG8_SCHED;
	s_setprio 0
	s_add_i32 s69, s57, s48
	v_lshl_add_u64 v[144:145], s[40:41], 0, v[132:133]
	s_mov_b32 m0, s69
	ds_read_b128 v[186:189], v151 offset:16384
	ds_read_b128 v[190:193], v151 offset:17408
	ds_read_b128 v[194:197], v151 offset:18432
	ds_read_b128 v[198:201], v151 offset:19456
	ds_read_b128 v[202:205], v151 offset:20480
	ds_read_b128 v[206:209], v151 offset:21504
	ds_read_b128 v[210:213], v151 offset:22528
	ds_read_b128 v[214:217], v151 offset:23552
	global_load_lds_dwordx4 v[144:145], off
	s_add_i32 m0, s69, 0x2000
	s_add_u32 s70, s40, 0x40000
	v_lshl_add_u64 v[218:219], s[40:41], 0, v[128:129]
	s_addc_u32 s71, s41, 0
	s_add_i32 s69, s58, s48
	global_load_lds_dwordx4 v[218:219], off
	v_lshl_add_u64 v[220:221], s[70:71], 0, v[132:133]
	s_mov_b32 m0, s69
	v_lshl_add_u64 v[222:223], s[42:43], 0, v[130:131]
	global_load_lds_dwordx4 v[220:221], off
	v_lshl_add_u64 v[220:221], s[70:71], 0, v[128:129]
	s_add_i32 m0, s69, 0x2000
	s_nop 0
	global_load_lds_dwordx4 v[220:221], off
	v_lshl_add_u64 v[220:221], s[42:43], 0, v[134:135]
	s_mov_b32 m0, s37
	s_nop 0
	global_load_lds_dwordx4 v[220:221], off
	s_mov_b32 m0, s50
	s_nop 0
	global_load_lds_dwordx4 v[222:223], off
	s_waitcnt vmcnt(14)
	s_waitcnt lgkmcnt(0)
	s_barrier
	s_setprio 1
	v_mfma_f32_16x16x32_bf16 v[60:63], v[154:157], v[186:189], 0
	v_mfma_f32_16x16x32_bf16 v[52:55], v[162:165], v[186:189], 0
	v_mfma_f32_16x16x32_bf16 v[44:47], v[154:157], v[194:197], 0
	v_mfma_f32_16x16x32_bf16 v[36:39], v[162:165], v[194:197], 0
	v_mfma_f32_16x16x32_bf16 v[28:31], v[154:157], v[202:205], 0
	v_mfma_f32_16x16x32_bf16 v[20:23], v[162:165], v[202:205], 0
	v_mfma_f32_16x16x32_bf16 v[12:15], v[154:157], v[210:213], 0
	v_mfma_f32_16x16x32_bf16 v[4:7], v[162:165], v[210:213], 0
	v_mfma_f32_16x16x32_bf16 v[60:63], v[158:161], v[190:193], v[60:63]
	v_mfma_f32_16x16x32_bf16 v[52:55], v[166:169], v[190:193], v[52:55]
	v_mfma_f32_16x16x32_bf16 v[44:47], v[158:161], v[198:201], v[44:47]
	v_mfma_f32_16x16x32_bf16 v[36:39], v[166:169], v[198:201], v[36:39]
	v_mfma_f32_16x16x32_bf16 v[28:31], v[158:161], v[206:209], v[28:31]
	v_mfma_f32_16x16x32_bf16 v[20:23], v[166:169], v[206:209], v[20:23]
	v_mfma_f32_16x16x32_bf16 v[12:15], v[158:161], v[214:217], v[12:15]
	v_mfma_f32_16x16x32_bf16 v[4:7], v[166:169], v[214:217], v[4:7]
	v_mfma_f32_16x16x32_bf16 v[56:59], v[170:173], v[186:189], 0
	v_mfma_f32_16x16x32_bf16 v[48:51], v[178:181], v[186:189], 0
	v_mfma_f32_16x16x32_bf16 v[40:43], v[170:173], v[194:197], 0
	v_mfma_f32_16x16x32_bf16 v[32:35], v[178:181], v[194:197], 0
	v_mfma_f32_16x16x32_bf16 v[24:27], v[170:173], v[202:205], 0
	v_mfma_f32_16x16x32_bf16 v[16:19], v[178:181], v[202:205], 0
	v_mfma_f32_16x16x32_bf16 v[8:11], v[170:173], v[210:213], 0
	v_mfma_f32_16x16x32_bf16 v[0:3], v[178:181], v[210:213], 0
	v_mfma_f32_16x16x32_bf16 v[56:59], v[174:177], v[190:193], v[56:59]
	v_mfma_f32_16x16x32_bf16 v[48:51], v[182:185], v[190:193], v[48:51]
	v_mfma_f32_16x16x32_bf16 v[40:43], v[174:177], v[198:201], v[40:43]
	v_mfma_f32_16x16x32_bf16 v[32:35], v[182:185], v[198:201], v[32:35]
	v_mfma_f32_16x16x32_bf16 v[24:27], v[174:177], v[206:209], v[24:27]
	v_mfma_f32_16x16x32_bf16 v[16:19], v[182:185], v[206:209], v[16:19]
	v_mfma_f32_16x16x32_bf16 v[8:11], v[174:177], v[214:217], v[8:11]
	v_mfma_f32_16x16x32_bf16 v[0:3], v[182:185], v[214:217], v[0:3]
	s_barrier
	s_setprio 0
	s_add_i32 s69, 0, 0x18000
	v_add_u32_e32 v153, s69, v147
	s_add_i32 s70, 0, 0x1c000
	ds_read_b128 v[154:157], v153
	ds_read_b128 v[158:161], v153 offset:1024
	ds_read_b128 v[162:165], v153 offset:2048
	ds_read_b128 v[166:169], v153 offset:3072
	v_add_u32_e32 v153, s70, v147
	ds_read_b128 v[170:173], v153
	ds_read_b128 v[174:177], v153 offset:1024
	ds_read_b128 v[178:181], v153 offset:2048
	ds_read_b128 v[182:185], v153 offset:3072
	s_add_u32 s42, s42, 0x40000
	s_addc_u32 s43, s43, 0
	s_mov_b32 m0, s51
	v_lshl_add_u64 v[224:225], s[42:43], 0, v[134:135]
	ds_read_b128 v[186:189], v151 offset:32768
	ds_read_b128 v[190:193], v151 offset:33792
	ds_read_b128 v[194:197], v151 offset:34816
	ds_read_b128 v[198:201], v151 offset:35840
	ds_read_b128 v[202:205], v151 offset:36864
	ds_read_b128 v[206:209], v151 offset:37888
	ds_read_b128 v[210:213], v151 offset:38912
	ds_read_b128 v[214:217], v151 offset:39936
	global_load_lds_dwordx4 v[224:225], off
	v_lshl_add_u64 v[224:225], s[42:43], 0, v[130:131]
	s_mov_b32 m0, s52
	s_nop 0
	global_load_lds_dwordx4 v[224:225], off
	s_waitcnt vmcnt(16)
	s_waitcnt lgkmcnt(0)
	s_barrier
; #define PG8_STAGE(bufoff, gbase, voff) do { _Pragma("unroll") for (int _i = 0; _i < 2; ++_i) \
;         __builtin_amdgcn_global_load_lds((const unsigned*)((const char*)(gbase) + (voff)[_i]), (PG8_LAS unsigned*)(lds + (bufoff) + ldsw + _i * 8192), 16, 0, 0); } while (0)
; #define PG8_LDA(dst, b, h) do { _Pragma("unroll") for (int m = 0; m < 4; ++m) _Pragma("unroll") for (int k = 0; k < 2; ++k) dst[m][k] = *(const PG8_LAS bf16x8*)(lds + PG8_SA(b, h) + aoff + m * 2048 + k * 1024); } while (0)
; #define PG8_MMA(ai, bj, At, Bt) do { __builtin_amdgcn_s_setprio(1); _Pragma("unroll") for (int m = 0; m < 4; ++m) _Pragma("unroll") for (int n = 0; n < 2; ++n) _Pragma("unroll") for (int k = 0; k < 2; ++k) \
;         acc[ai][bj][m][n] = __builtin_amdgcn_mfma_f32_16x16x32_bf16(Bt[n][k], At[m][k], acc[ai][bj][m][n], 0, 0, 0); __builtin_amdgcn_s_setprio(0); } while (0)
; #define PG8_WAIT_V(n) asm volatile("s_waitcnt vmcnt(" #n ")" ::: "memory")
; #define PG8_WAIT_L(n) asm volatile("s_waitcnt lgkmcnt(" #n ")" ::: "memory")
; #define PG8_BAR __builtin_amdgcn_s_barrier()
; #define PG8_SCHED __builtin_amdgcn_sched_barrier(0)
; template <class Epi, class Sched, bool ALIGN_EPI = false, bool SP2 = false>
; __device__ __forceinline__ void gemm_phase(PG8_LAS unsigned char* lds, const Gemm g, const Sched& S, const Epi& E) {
;     ...
;             PG8_WAIT_V(8); PG8_WAIT_L(0); PG8_BAR; PG8_MMA(0, 0, At, B0); PG8_MMA(0, 1, At, B1); PG8_BAR; PG8_SCHED;
;             PG8_LDA(At, 1, 1); PG8_STAGE(PG8_SB(1, 0), b3, voffB); PG8_STAGE(PG8_SB(1, 1), b3 + hstep, voffB); PG8_STAGE(PG8_SA(1, 0), a3, voffA);
;             PG8_WAIT_V(8); PG8_WAIT_L(0); PG8_BAR; PG8_MMA(1, 0, At, B0); PG8_MMA(1, 1, At, B1); PG8_BAR; PG8_SCHED;
	s_setprio 1
	v_mfma_f32_16x16x32_bf16 v[120:123], v[154:157], v[186:189], v[120:123]
	v_mfma_f32_16x16x32_bf16 v[116:119], v[162:165], v[186:189], v[116:119]
	v_mfma_f32_16x16x32_bf16 v[108:111], v[154:157], v[194:197], v[108:111]
	v_mfma_f32_16x16x32_bf16 v[100:103], v[162:165], v[194:197], v[100:103]
	v_mfma_f32_16x16x32_bf16 v[92:95], v[154:157], v[202:205], v[92:95]
	v_mfma_f32_16x16x32_bf16 v[84:87], v[162:165], v[202:205], v[84:87]
	v_mfma_f32_16x16x32_bf16 v[76:79], v[154:157], v[210:213], v[76:79]
	v_mfma_f32_16x16x32_bf16 v[68:71], v[162:165], v[210:213], v[68:71]
	v_mfma_f32_16x16x32_bf16 v[120:123], v[158:161], v[190:193], v[120:123]
	v_mfma_f32_16x16x32_bf16 v[116:119], v[166:169], v[190:193], v[116:119]
	v_mfma_f32_16x16x32_bf16 v[108:111], v[158:161], v[198:201], v[108:111]
	v_mfma_f32_16x16x32_bf16 v[100:103], v[166:169], v[198:201], v[100:103]
	v_mfma_f32_16x16x32_bf16 v[92:95], v[158:161], v[206:209], v[92:95]
	v_mfma_f32_16x16x32_bf16 v[84:87], v[166:169], v[206:209], v[84:87]
	v_mfma_f32_16x16x32_bf16 v[76:79], v[158:161], v[214:217], v[76:79]
	v_mfma_f32_16x16x32_bf16 v[68:71], v[166:169], v[214:217], v[68:71]
	v_mfma_f32_16x16x32_bf16 v[124:127], v[170:173], v[186:189], v[124:127]
	v_mfma_f32_16x16x32_bf16 v[112:115], v[178:181], v[186:189], v[112:115]
	v_mfma_f32_16x16x32_bf16 v[104:107], v[170:173], v[194:197], v[104:107]
	v_mfma_f32_16x16x32_bf16 v[96:99], v[178:181], v[194:197], v[96:99]
	v_mfma_f32_16x16x32_bf16 v[88:91], v[170:173], v[202:205], v[88:91]
	v_mfma_f32_16x16x32_bf16 v[80:83], v[178:181], v[202:205], v[80:83]
	v_mfma_f32_16x16x32_bf16 v[72:75], v[170:173], v[210:213], v[72:75]
	v_mfma_f32_16x16x32_bf16 v[64:67], v[178:181], v[210:213], v[64:67]
	v_mfma_f32_16x16x32_bf16 v[124:127], v[174:177], v[190:193], v[124:127]
	v_mfma_f32_16x16x32_bf16 v[112:115], v[182:185], v[190:193], v[112:115]
	v_mfma_f32_16x16x32_bf16 v[104:107], v[174:177], v[198:201], v[104:107]
	v_mfma_f32_16x16x32_bf16 v[96:99], v[182:185], v[198:201], v[96:99]
	v_mfma_f32_16x16x32_bf16 v[88:91], v[174:177], v[206:209], v[88:91]
	v_mfma_f32_16x16x32_bf16 v[80:83], v[182:185], v[206:209], v[80:83]
	v_mfma_f32_16x16x32_bf16 v[72:75], v[174:177], v[214:217], v[72:75]
	v_mfma_f32_16x16x32_bf16 v[64:67], v[182:185], v[214:217], v[64:67]
	s_barrier
	s_setprio 0
	s_add_i32 s42, s69, s48
	v_lshl_add_u64 v[144:145], v[144:145], 0, s[14:15]
	s_mov_b32 m0, s42
	ds_read_b128 v[186:189], v151 offset:49152
	ds_read_b128 v[190:193], v151 offset:50176
	ds_read_b128 v[194:197], v151 offset:51200
	ds_read_b128 v[198:201], v151 offset:52224
	ds_read_b128 v[202:205], v151 offset:53248
	ds_read_b128 v[206:209], v151 offset:54272
	ds_read_b128 v[210:213], v151 offset:55296
	ds_read_b128 v[214:217], v151 offset:56320
	global_load_lds_dwordx4 v[144:145], off
	s_add_i32 m0, s42, 0x2000
	s_add_u32 s40, s40, 0x40080
	v_lshl_add_u64 v[144:145], v[218:219], 0, s[14:15]
	s_addc_u32 s41, s41, 0
	s_add_i32 s42, s70, s48
	global_load_lds_dwordx4 v[144:145], off
	v_lshl_add_u64 v[144:145], s[40:41], 0, v[132:133]
	s_mov_b32 m0, s42
	s_nop 0
	global_load_lds_dwordx4 v[144:145], off
	v_lshl_add_u64 v[144:145], s[40:41], 0, v[128:129]
	s_add_i32 m0, s42, 0x2000
	s_nop 0
	global_load_lds_dwordx4 v[144:145], off
	v_lshl_add_u64 v[144:145], v[220:221], 0, s[14:15]
	s_mov_b32 m0, s53
	s_nop 0
	global_load_lds_dwordx4 v[144:145], off
	v_lshl_add_u64 v[144:145], v[222:223], 0, s[14:15]
	s_mov_b32 m0, s54
	s_nop 0
	global_load_lds_dwordx4 v[144:145], off
	s_waitcnt vmcnt(8)
	s_waitcnt lgkmcnt(0)
	s_barrier
	s_setprio 1
	v_mfma_f32_16x16x32_bf16 v[60:63], v[154:157], v[186:189], v[60:63]
	v_mfma_f32_16x16x32_bf16 v[52:55], v[162:165], v[186:189], v[52:55]
	v_mfma_f32_16x16x32_bf16 v[44:47], v[154:157], v[194:197], v[44:47]
	v_mfma_f32_16x16x32_bf16 v[36:39], v[162:165], v[194:197], v[36:39]
	v_mfma_f32_16x16x32_bf16 v[28:31], v[154:157], v[202:205], v[28:31]
	v_mfma_f32_16x16x32_bf16 v[20:23], v[162:165], v[202:205], v[20:23]
	v_mfma_f32_16x16x32_bf16 v[12:15], v[154:157], v[210:213], v[12:15]
	v_mfma_f32_16x16x32_bf16 v[4:7], v[162:165], v[210:213], v[4:7]
	v_mfma_f32_16x16x32_bf16 v[60:63], v[158:161], v[190:193], v[60:63]
	v_mfma_f32_16x16x32_bf16 v[52:55], v[166:169], v[190:193], v[52:55]
	v_mfma_f32_16x16x32_bf16 v[44:47], v[158:161], v[198:201], v[44:47]
	v_mfma_f32_16x16x32_bf16 v[36:39], v[166:169], v[198:201], v[36:39]
	v_mfma_f32_16x16x32_bf16 v[28:31], v[158:161], v[206:209], v[28:31]
	v_mfma_f32_16x16x32_bf16 v[20:23], v[166:169], v[206:209], v[20:23]
	v_mfma_f32_16x16x32_bf16 v[12:15], v[158:161], v[214:217], v[12:15]
	v_mfma_f32_16x16x32_bf16 v[4:7], v[166:169], v[214:217], v[4:7]
	v_mfma_f32_16x16x32_bf16 v[56:59], v[170:173], v[186:189], v[56:59]
	v_mfma_f32_16x16x32_bf16 v[48:51], v[178:181], v[186:189], v[48:51]
	v_mfma_f32_16x16x32_bf16 v[40:43], v[170:173], v[194:197], v[40:43]
	v_mfma_f32_16x16x32_bf16 v[32:35], v[178:181], v[194:197], v[32:35]
	v_mfma_f32_16x16x32_bf16 v[24:27], v[170:173], v[202:205], v[24:27]
	v_mfma_f32_16x16x32_bf16 v[16:19], v[178:181], v[202:205], v[16:19]
	v_mfma_f32_16x16x32_bf16 v[8:11], v[170:173], v[210:213], v[8:11]
	v_mfma_f32_16x16x32_bf16 v[0:3], v[178:181], v[210:213], v[0:3]
	v_mfma_f32_16x16x32_bf16 v[56:59], v[174:177], v[190:193], v[56:59]
	v_mfma_f32_16x16x32_bf16 v[48:51], v[182:185], v[190:193], v[48:51]
	v_mfma_f32_16x16x32_bf16 v[40:43], v[174:177], v[198:201], v[40:43]
	v_mfma_f32_16x16x32_bf16 v[32:35], v[182:185], v[198:201], v[32:35]
	v_mfma_f32_16x16x32_bf16 v[24:27], v[174:177], v[206:209], v[24:27]
	v_mfma_f32_16x16x32_bf16 v[16:19], v[182:185], v[206:209], v[16:19]
	v_mfma_f32_16x16x32_bf16 v[8:11], v[174:177], v[214:217], v[8:11]
	v_mfma_f32_16x16x32_bf16 v[0:3], v[182:185], v[214:217], v[0:3]
	s_barrier
	s_setprio 0
	s_add_i32 s68, s68, 2
	s_add_u32 s38, s38, 0x100
	s_addc_u32 s39, s39, 0
	s_add_u32 s66, s66, 0x100
	s_addc_u32 s67, s67, 0

; #define PG8_STAGE(bufoff, gbase, voff) do { _Pragma("unroll") for (int _i = 0; _i < 2; ++_i) \
;         __builtin_amdgcn_global_load_lds((const unsigned*)((const char*)(gbase) + (voff)[_i]), (PG8_LAS unsigned*)(lds + (bufoff) + ldsw + _i * 8192), 16, 0, 0); } while (0)
; #define PG8_WAIT_V(n) asm volatile("s_waitcnt vmcnt(" #n ")" ::: "memory")
; #define PG8_BAR __builtin_amdgcn_s_barrier()
; template <class Epi, class Sched, bool ALIGN_EPI = false, bool SP2 = false>
; __device__ __forceinline__ void gemm_phase(PG8_LAS unsigned char* lds, const Gemm g, const Sched& S, const Epi& E) {
;     const int tid = threadIdx.x, wid = __builtin_amdgcn_readfirstlane(tid >> 6), lane = tid & 63, wr = wid >> 2, wc = wid & 3, fr = lane & 15, fq = lane >> 4;
;     const int K = g.K, nt = K / BK;
;     unsigned voffA[2], voffB[2];
; #pragma unroll
;     for (int i = 0; i < 2; ++i) { int R, C; stage_rc(tid * 16 + i * 8192, R, C); const int Rb = Epi::PERM ? ((R & ~31) + perm32(R & 31)) : R;
;         voffA[i] = (unsigned)(R * K + C) * 2u; voffB[i] = (unsigned)(Rb * K + C) * 2u; }
;     const size_t kstep = (size_t)(BK * 2);
;     const size_t hstep = (size_t)HALF * K * 2;
;     const size_t tstep = 2 * hstep;
;     const unsigned ldsw = (unsigned)wid * 1024u;
;     const int aoff = lds_byte(wr * 64 + fr, fq * 8), boff = lds_byte(wc * 32 + fr, fq * 8);
;     ...
;         PG8_WAIT_V(2); PG8_BAR;
;         PG8_STAGE(PG8_SB(1, 0), cB + kstep, voffB); PG8_STAGE(PG8_SA(1, 0), cA + kstep, voffA); PG8_STAGE(PG8_SB(1, 1), cB + hstep + kstep, voffB);
;         PG8_WAIT_V(6); PG8_BAR;
.LBB0_1544:
	s_mul_i32 s12, s12, s8
	s_sub_i32 s9, s9, s12
	s_sub_i32 s12, s9, s8
	s_cmp_ge_u32 s9, s8
	s_cselect_b32 s9, s12, s9
	s_sub_i32 s12, s9, s8
	s_cmp_ge_u32 s9, s8
	s_cselect_b32 s8, s12, s9
	s_xor_b32 s8, s8, s3
	s_sub_i32 s8, s8, s3
	s_ashr_i32 s9, s8, 31
	s_and_b64 s[12:13], s[30:31], exec
	s_cselect_b32 s12, 25, 28
	s_lshl_b64 s[12:13], s[8:9], s12
	s_add_u32 s15, s4, s12
	s_addc_u32 s19, s5, s13
	s_and_b64 s[12:13], s[30:31], exec
	s_cselect_b32 s12, 12, 15
	s_lshl_b64 s[8:9], s[8:9], s12
	s_mul_hi_u32 s12, s8, 0xffffea00
	s_sub_i32 s12, s12, s8
	s_mulk_i32 s9, 0xea00
	s_add_i32 s12, s12, s9
	s_mulk_i32 s8, 0xea00
	s_add_u32 s8, s15, s8
	s_addc_u32 s9, s19, s12
	s_add_u32 s8, s8, 0xa000000
	s_addc_u32 s9, s9, 0
	s_add_u32 s12, s4, 0x5c0000
	s_addc_u32 s13, s5, 0
	s_lshl_b32 s4, s14, 5
	s_mov_b64 s[14:15], 0x80
	s_and_b32 s20, s4, 0x60
	s_add_i32 m0, s37, 0x18000
	v_lshl_add_u64 v[6:7], v[6:7], 0, s[14:15]
	s_lshl_b32 s19, s18, 13
	s_lshl_b32 s21, s20, 7
	s_waitcnt vmcnt(2)
	s_barrier
	global_load_lds_dwordx4 v[6:7], off
	v_lshl_add_u64 v[4:5], v[4:5], 0, s[14:15]
	s_add_i32 m0, s37, 0x1a000
	s_add_i32 s53, s37, 0x8000
	s_add_i32 s54, s37, 0xa000
	global_load_lds_dwordx4 v[4:5], off
	v_lshl_add_u64 v[0:1], v[0:1], 0, s[14:15]
	s_mov_b32 m0, s53
	s_add_u32 s4, s40, 0x40080
	global_load_lds_dwordx4 v[0:1], off
	v_lshl_add_u64 v[0:1], v[2:3], 0, s[14:15]
	s_mov_b32 m0, s54
	s_addc_u32 s5, s41, 0
	global_load_lds_dwordx4 v[0:1], off
	s_add_i32 m0, s37, 0x1c000
	v_lshl_add_u64 v[0:1], s[4:5], 0, v[132:133]
	global_load_lds_dwordx4 v[0:1], off
	v_lshl_add_u64 v[0:1], s[4:5], 0, v[128:129]
	s_add_i32 m0, s37, 0x1e000
	v_lshlrev_b32_e32 v2, 2, v242
	global_load_lds_dwordx4 v[0:1], off
	v_and_b32_e32 v0, 15, v242
	v_lshlrev_b32_e32 v1, 1, v11
	v_lshlrev_b32_e32 v3, 6, v242
	s_movk_i32 s4, 0x3c0
	v_lshl_or_b32 v146, s18, 6, v0
	v_lshl_or_b32 v0, v0, 6, v1
	v_and_b32_e32 v2, 32, v2
	v_and_or_b32 v1, v3, s4, v1
	v_bitop3_b32 v147, s21, v1, v2 bitop3:0xf6
	v_lshlrev_b32_e32 v1, 8, v242
	v_bitop3_b32 v0, v0, s19, v2 bitop3:0xde
	v_and_b32_e32 v1, 0x38000, v1
	v_lshlrev_b32_e32 v2, 11, v12
	v_or3_b32 v1, v9, v1, v2
	v_add_u32_e32 v136, v1, v10
	v_lshlrev_b32_e32 v1, 4, v8
	s_waitcnt vmcnt(6)
	s_cmpk_lt_u32 s17, 0x100
	v_and_b32_e32 v1, 0x78000, v1
	s_sext_i32_i16 s63, s16
	s_cselect_b64 s[16:17], -1, 0
	v_or3_b32 v1, v9, v1, v2
	s_add_i32 s57, 0, 0x10000
	s_add_i32 s58, 0, 0x14000
	s_mov_b32 s55, 0
	s_ashr_i32 s56, s61, 31
	v_or_b32_e32 v148, s20, v11
	v_mov_b32_e32 v137, v133
	v_add_u32_e32 v138, v1, v10
	v_mov_b32_e32 v139, v133
	v_mov_b64_e32 v[140:141], 0xb00
	v_mov_b64_e32 v[142:143], 0xaff
	v_add_u32_e32 v149, s57, v147
	v_add_u32_e32 v150, s58, v147
	v_add_u32_e32 v151, 0, v0
	v_mov_b32_e32 v152, 0x358637bd
	s_movk_i32 s59, 0x1600
	s_barrier
	s_mov_b32 s99, 1
	s_branch .LBB0_1547

; #define PG8_STAGE(bufoff, gbase, voff) do { _Pragma("unroll") for (int _i = 0; _i < 2; ++_i) \
;         __builtin_amdgcn_global_load_lds((const unsigned*)((const char*)(gbase) + (voff)[_i]), (PG8_LAS unsigned*)(lds + (bufoff) + ldsw + _i * 8192), 16, 0, 0); } while (0)
; #define PG8_WAIT_V(n) asm volatile("s_waitcnt vmcnt(" #n ")" ::: "memory")
; #define PG8_BAR __builtin_amdgcn_s_barrier()
; template <class Epi, class Sched, bool ALIGN_EPI = false, bool SP2 = false>
; __device__ __forceinline__ void gemm_phase(PG8_LAS unsigned char* lds, const Gemm g, const Sched& S, const Epi& E) {
;     const int tid = threadIdx.x, wid = __builtin_amdgcn_readfirstlane(tid >> 6), lane = tid & 63, wr = wid >> 2, wc = wid & 3, fr = lane & 15, fq = lane >> 4;
;     const int K = g.K, nt = K / BK;
;     unsigned voffA[2], voffB[2];
; #pragma unroll
;     for (int i = 0; i < 2; ++i) { int R, C; stage_rc(tid * 16 + i * 8192, R, C); const int Rb = Epi::PERM ? ((R & ~31) + perm32(R & 31)) : R;
;         voffA[i] = (unsigned)(R * K + C) * 2u; voffB[i] = (unsigned)(Rb * K + C) * 2u; }
;     const size_t kstep = (size_t)(BK * 2);
;     const size_t hstep = (size_t)HALF * K * 2;
;     const size_t tstep = 2 * hstep;
;     const unsigned ldsw = (unsigned)wid * 1024u;
;     const int aoff = lds_byte(wr * 64 + fr, fq * 8), boff = lds_byte(wc * 32 + fr, fq * 8);
;     ...
;         PG8_WAIT_V(2); PG8_BAR;
;         PG8_STAGE(PG8_SB(1, 0), cB + kstep, voffB); PG8_STAGE(PG8_SA(1, 0), cA + kstep, voffA); PG8_STAGE(PG8_SB(1, 1), cB + hstep + kstep, voffB);
;         PG8_WAIT_V(6); PG8_BAR;
.LBB0_2416:
	s_mul_i32 s12, s12, s8
	s_sub_i32 s9, s9, s12
	s_sub_i32 s12, s9, s8
	s_cmp_ge_u32 s9, s8
	s_cselect_b32 s9, s12, s9
	s_sub_i32 s12, s9, s8
	s_cmp_ge_u32 s9, s8
	s_cselect_b32 s8, s12, s9
	s_xor_b32 s8, s8, s3
	s_sub_i32 s8, s8, s3
	s_ashr_i32 s9, s8, 31
	s_and_b64 s[12:13], s[30:31], exec
	s_cselect_b32 s12, 25, 28
	s_lshl_b64 s[12:13], s[8:9], s12
	s_add_u32 s15, s4, s12
	s_addc_u32 s19, s5, s13
	s_and_b64 s[12:13], s[30:31], exec
	s_cselect_b32 s12, 12, 15
	s_lshl_b64 s[8:9], s[8:9], s12
	s_mul_hi_u32 s12, s8, 0xffffea00
	s_sub_i32 s12, s12, s8
	s_mulk_i32 s9, 0xea00
	s_add_i32 s12, s12, s9
	s_mulk_i32 s8, 0xea00
	s_add_u32 s8, s15, s8
	s_addc_u32 s9, s19, s12
	s_add_u32 s8, s8, 0xa000000
	s_addc_u32 s9, s9, 0
	s_add_u32 s12, s4, 0x640000
	s_addc_u32 s13, s5, 0
	s_lshl_b32 s4, s14, 5
	s_mov_b64 s[14:15], 0x80
	s_and_b32 s20, s4, 0x60
	s_add_i32 m0, s37, 0x18000
	v_lshl_add_u64 v[6:7], v[6:7], 0, s[14:15]
	s_lshl_b32 s19, s18, 13
	s_lshl_b32 s21, s20, 7
	s_waitcnt vmcnt(2)
	s_barrier
	global_load_lds_dwordx4 v[6:7], off
	v_lshl_add_u64 v[4:5], v[4:5], 0, s[14:15]
	s_add_i32 m0, s37, 0x1a000
	s_add_i32 s53, s37, 0x8000
	s_add_i32 s54, s37, 0xa000
	global_load_lds_dwordx4 v[4:5], off
	v_lshl_add_u64 v[0:1], v[0:1], 0, s[14:15]
	s_mov_b32 m0, s53
	s_add_u32 s4, s40, 0x40080
	global_load_lds_dwordx4 v[0:1], off
	v_lshl_add_u64 v[0:1], v[2:3], 0, s[14:15]
	s_mov_b32 m0, s54
	s_addc_u32 s5, s41, 0
	global_load_lds_dwordx4 v[0:1], off
	s_add_i32 m0, s37, 0x1c000
	v_lshl_add_u64 v[0:1], s[4:5], 0, v[132:133]
	global_load_lds_dwordx4 v[0:1], off
	v_lshl_add_u64 v[0:1], s[4:5], 0, v[128:129]
	s_add_i32 m0, s37, 0x1e000
	v_lshlrev_b32_e32 v2, 2, v242
	global_load_lds_dwordx4 v[0:1], off
	v_and_b32_e32 v0, 15, v242
	v_lshlrev_b32_e32 v1, 1, v11
	v_lshlrev_b32_e32 v3, 6, v242
	s_movk_i32 s4, 0x3c0
	v_lshl_or_b32 v146, s18, 6, v0
	v_lshl_or_b32 v0, v0, 6, v1
	v_and_b32_e32 v2, 32, v2
	v_and_or_b32 v1, v3, s4, v1
	v_bitop3_b32 v147, s21, v1, v2 bitop3:0xf6
	v_lshlrev_b32_e32 v1, 8, v242
	v_bitop3_b32 v0, v0, s19, v2 bitop3:0xde
	v_and_b32_e32 v1, 0x38000, v1
	v_lshlrev_b32_e32 v2, 11, v12
	v_or3_b32 v1, v9, v1, v2
	v_add_u32_e32 v136, v1, v10
	v_lshlrev_b32_e32 v1, 4, v8
	s_waitcnt vmcnt(6)
	s_cmpk_lt_u32 s17, 0x100
	v_and_b32_e32 v1, 0x78000, v1
	s_sext_i32_i16 s63, s16
	s_cselect_b64 s[16:17], -1, 0
	v_or3_b32 v1, v9, v1, v2
	s_add_i32 s57, 0, 0x10000
	s_add_i32 s58, 0, 0x14000
	s_mov_b32 s55, 0
	s_ashr_i32 s56, s61, 31
	v_or_b32_e32 v148, s20, v11
	v_mov_b32_e32 v137, v133
	v_add_u32_e32 v138, v1, v10
	v_mov_b32_e32 v139, v133
	v_mov_b64_e32 v[140:141], 0xb00
	v_mov_b64_e32 v[142:143], 0xaff
	v_add_u32_e32 v149, s57, v147
	v_add_u32_e32 v150, s58, v147
	v_add_u32_e32 v151, 0, v0
	v_mov_b32_e32 v152, 0x358637bd
	s_movk_i32 s59, 0x1600
	s_barrier
	s_mov_b32 s99, 1
	s_branch .LBB0_2419
